# EpiResid start: counted vmcnt for gate params #1 (xb rows stay in flight), params #2 issued under xb latency; out-GEMM xb loads moved ahead of first wait
# speedup vs baseline: 1.0086x; 1.0015x over previous
.LBB0_374:
	s_add_u32 s16, s14, 0x100
	s_addc_u32 s17, s15, 0
	s_add_i32 s49, 0, 0x10000
	v_add_u32_e32 v154, s49, v164
	ds_read_b128 v[142:145], v154
	ds_read_b128 v[146:149], v154 offset:1024
	ds_read_b128 v[150:153], v154 offset:2048
	ds_read_b128 v[154:157], v154 offset:3072
	s_cmp_eq_u32 s48, 40
	s_cselect_b32 s21, s7, s17
	s_cselect_b32 s20, s6, s16
	s_cselect_b32 s19, s9, s47
	s_cselect_b32 s18, s8, s46
	v_lshl_add_u64 v[162:163], s[14:15], 0, v[138:139]
	s_add_i32 m0, s35, 0xc000
	ds_read_b128 v[158:161], v166
	ds_read_b128 v[168:171], v166 offset:1024
	ds_read_b128 v[172:175], v166 offset:2048
	ds_read_b128 v[190:193], v166 offset:3072
	ds_read_b128 v[194:197], v166 offset:4096
	ds_read_b128 v[198:201], v166 offset:5120
	ds_read_b128 v[202:205], v166 offset:6144
	ds_read_b128 v[206:209], v166 offset:7168
	global_load_lds_dwordx4 v[162:163], off
	v_lshl_add_u64 v[162:163], s[14:15], 0, v[140:141]
	s_add_i32 m0, s35, 0xe000
	s_nop 0
	global_load_lds_dwordx4 v[162:163], off
	s_waitcnt lgkmcnt(8)
	s_barrier
	s_waitcnt lgkmcnt(0)
	s_waitcnt lgkmcnt(0)
	v_mfma_f32_16x16x32_bf16 v[126:129], v[142:145], v[158:161], v[126:129]
	v_mfma_f32_16x16x32_bf16 v[122:125], v[150:153], v[158:161], v[122:125]
	v_mfma_f32_16x16x32_bf16 v[110:113], v[142:145], v[172:175], v[110:113]
	v_mfma_f32_16x16x32_bf16 v[106:109], v[150:153], v[172:175], v[106:109]
	v_mfma_f32_16x16x32_bf16 v[94:97], v[142:145], v[194:197], v[94:97]
	v_mfma_f32_16x16x32_bf16 v[90:93], v[150:153], v[194:197], v[90:93]
	v_mfma_f32_16x16x32_bf16 v[78:81], v[142:145], v[202:205], v[78:81]
	v_mfma_f32_16x16x32_bf16 v[74:77], v[150:153], v[202:205], v[74:77]
	v_mfma_f32_16x16x32_bf16 v[126:129], v[146:149], v[168:171], v[126:129]
	v_mfma_f32_16x16x32_bf16 v[122:125], v[154:157], v[168:171], v[122:125]
	v_mfma_f32_16x16x32_bf16 v[110:113], v[146:149], v[190:193], v[110:113]
	v_mfma_f32_16x16x32_bf16 v[106:109], v[154:157], v[190:193], v[106:109]
	v_mfma_f32_16x16x32_bf16 v[94:97], v[146:149], v[198:201], v[94:97]
	v_mfma_f32_16x16x32_bf16 v[90:93], v[154:157], v[198:201], v[90:93]
	v_mfma_f32_16x16x32_bf16 v[78:81], v[146:149], v[206:209], v[78:81]
	v_mfma_f32_16x16x32_bf16 v[74:77], v[154:157], v[206:209], v[74:77]
	s_barrier
	s_add_i32 s50, 0, 0x14000
	v_add_u32_e32 v162, s50, v164
	s_add_i32 s14, s49, s34
	ds_read_b128 v[210:213], v162
	ds_read_b128 v[214:217], v162 offset:1024
	ds_read_b128 v[218:221], v162 offset:2048
	ds_read_b128 v[222:225], v162 offset:3072
	s_add_u32 s64, s18, 0x80
	s_addc_u32 s65, s19, 0
	s_mov_b32 m0, s14
	s_nop 0
	global_load_lds_dwordx4 v132, s[18:19]
	s_add_i32 m0, s14, 0x2000
	s_nop 0
	global_load_lds_dwordx4 v136, s[18:19]
	s_barrier
	s_waitcnt lgkmcnt(0)
	s_waitcnt lgkmcnt(0)
	v_mfma_f32_16x16x32_bf16 v[118:121], v[210:213], v[158:161], v[118:121]
	v_mfma_f32_16x16x32_bf16 v[114:117], v[218:221], v[158:161], v[114:117]
	v_mfma_f32_16x16x32_bf16 v[102:105], v[210:213], v[172:175], v[102:105]
	v_mfma_f32_16x16x32_bf16 v[98:101], v[218:221], v[172:175], v[98:101]
	v_mfma_f32_16x16x32_bf16 v[86:89], v[210:213], v[194:197], v[86:89]
	v_mfma_f32_16x16x32_bf16 v[82:85], v[218:221], v[194:197], v[82:85]
	v_mfma_f32_16x16x32_bf16 v[70:73], v[210:213], v[202:205], v[70:73]
	v_mfma_f32_16x16x32_bf16 v[66:69], v[218:221], v[202:205], v[66:69]
	v_mfma_f32_16x16x32_bf16 v[118:121], v[214:217], v[168:171], v[118:121]
	v_mfma_f32_16x16x32_bf16 v[114:117], v[222:225], v[168:171], v[114:117]
	v_mfma_f32_16x16x32_bf16 v[102:105], v[214:217], v[190:193], v[102:105]
	v_mfma_f32_16x16x32_bf16 v[98:101], v[222:225], v[190:193], v[98:101]
	v_mfma_f32_16x16x32_bf16 v[86:89], v[214:217], v[198:201], v[86:89]
	v_mfma_f32_16x16x32_bf16 v[82:85], v[222:225], v[198:201], v[82:85]
	v_mfma_f32_16x16x32_bf16 v[70:73], v[214:217], v[206:209], v[70:73]
	v_mfma_f32_16x16x32_bf16 v[66:69], v[222:225], v[206:209], v[66:69]
	s_barrier
	s_mov_b32 m0, s35
	s_add_u32 s62, s20, 0x80
	s_addc_u32 s63, s21, 0
	ds_read_b128 v[158:161], v166 offset:16384
	ds_read_b128 v[168:171], v166 offset:17408
	ds_read_b128 v[172:175], v166 offset:18432
	ds_read_b128 v[190:193], v166 offset:19456
	ds_read_b128 v[194:197], v166 offset:20480
	ds_read_b128 v[198:201], v166 offset:21504
	ds_read_b128 v[202:205], v166 offset:22528
	ds_read_b128 v[206:209], v166 offset:23552
	global_load_lds_dwordx4 v130, s[20:21]
	s_mov_b32 m0, s36
	s_nop 0
	global_load_lds_dwordx4 v134, s[20:21]
	s_barrier
	s_waitcnt lgkmcnt(0)
	s_waitcnt lgkmcnt(0)
	v_mfma_f32_16x16x32_bf16 v[62:65], v[142:145], v[158:161], v[62:65]
	v_mfma_f32_16x16x32_bf16 v[58:61], v[150:153], v[158:161], v[58:61]
	v_mfma_f32_16x16x32_bf16 v[46:49], v[142:145], v[172:175], v[46:49]
	v_mfma_f32_16x16x32_bf16 v[42:45], v[150:153], v[172:175], v[42:45]
	v_mfma_f32_16x16x32_bf16 v[30:33], v[142:145], v[194:197], v[30:33]
	v_mfma_f32_16x16x32_bf16 v[26:29], v[150:153], v[194:197], v[26:29]
	v_mfma_f32_16x16x32_bf16 v[14:17], v[142:145], v[202:205], v[14:17]
	v_mfma_f32_16x16x32_bf16 v[10:13], v[150:153], v[202:205], v[10:13]
	v_mfma_f32_16x16x32_bf16 v[62:65], v[146:149], v[168:171], v[62:65]
	v_mfma_f32_16x16x32_bf16 v[58:61], v[154:157], v[168:171], v[58:61]
	v_mfma_f32_16x16x32_bf16 v[46:49], v[146:149], v[190:193], v[46:49]
	v_mfma_f32_16x16x32_bf16 v[42:45], v[154:157], v[190:193], v[42:45]
	v_mfma_f32_16x16x32_bf16 v[30:33], v[146:149], v[198:201], v[30:33]
	v_mfma_f32_16x16x32_bf16 v[26:29], v[154:157], v[198:201], v[26:29]
	v_mfma_f32_16x16x32_bf16 v[14:17], v[146:149], v[206:209], v[14:17]
	v_mfma_f32_16x16x32_bf16 v[10:13], v[154:157], v[206:209], v[10:13]
	s_barrier
	s_add_u32 s14, s18, 0xb0000
	s_addc_u32 s15, s19, 0
	s_add_i32 s49, s50, s34
	s_mov_b32 m0, s49
	s_nop 0
	global_load_lds_dwordx4 v132, s[14:15]
	s_add_i32 m0, s49, 0x2000
	s_nop 0
	global_load_lds_dwordx4 v136, s[14:15]
	s_waitcnt vmcnt(6)
	s_barrier
	v_mfma_f32_16x16x32_bf16 v[54:57], v[210:213], v[158:161], v[54:57]
	v_mfma_f32_16x16x32_bf16 v[50:53], v[218:221], v[158:161], v[50:53]
	v_mfma_f32_16x16x32_bf16 v[38:41], v[210:213], v[172:175], v[38:41]
	v_mfma_f32_16x16x32_bf16 v[34:37], v[218:221], v[172:175], v[34:37]
	v_mfma_f32_16x16x32_bf16 v[22:25], v[210:213], v[194:197], v[22:25]
	v_mfma_f32_16x16x32_bf16 v[18:21], v[218:221], v[194:197], v[18:21]
	v_mfma_f32_16x16x32_bf16 v[6:9], v[210:213], v[202:205], v[6:9]
	v_mfma_f32_16x16x32_bf16 v[2:5], v[218:221], v[202:205], v[2:5]
	v_mfma_f32_16x16x32_bf16 v[54:57], v[214:217], v[168:171], v[54:57]
	v_mfma_f32_16x16x32_bf16 v[50:53], v[222:225], v[168:171], v[50:53]
	v_mfma_f32_16x16x32_bf16 v[38:41], v[214:217], v[190:193], v[38:41]
	v_mfma_f32_16x16x32_bf16 v[34:37], v[222:225], v[190:193], v[34:37]
	v_mfma_f32_16x16x32_bf16 v[22:25], v[214:217], v[198:201], v[22:25]
	v_mfma_f32_16x16x32_bf16 v[18:21], v[222:225], v[198:201], v[18:21]
	v_mfma_f32_16x16x32_bf16 v[6:9], v[214:217], v[206:209], v[6:9]
	v_mfma_f32_16x16x32_bf16 v[2:5], v[222:225], v[206:209], v[2:5]
	s_barrier
	s_add_i32 s49, 0, 0x18000
	v_add_u32_e32 v154, s49, v164
	ds_read_b128 v[142:145], v154
	ds_read_b128 v[146:149], v154 offset:1024
	ds_read_b128 v[150:153], v154 offset:2048
	ds_read_b128 v[154:157], v154 offset:3072
	s_add_u32 s14, s20, 0xb8000
	s_addc_u32 s15, s21, 0
	s_mov_b32 m0, s37
	ds_read_b128 v[158:161], v166 offset:32768
	ds_read_b128 v[168:171], v166 offset:33792
	ds_read_b128 v[172:175], v166 offset:34816
	ds_read_b128 v[190:193], v166 offset:35840
	ds_read_b128 v[194:197], v166 offset:36864
	ds_read_b128 v[198:201], v166 offset:37888
	ds_read_b128 v[202:205], v166 offset:38912
	ds_read_b128 v[206:209], v166 offset:39936
	global_load_lds_dwordx4 v130, s[14:15]
	s_mov_b32 m0, s38
	s_nop 0
	global_load_lds_dwordx4 v134, s[14:15]
	s_waitcnt lgkmcnt(8)
	s_barrier
	s_waitcnt lgkmcnt(0)
	s_waitcnt lgkmcnt(0)
	v_mfma_f32_16x16x32_bf16 v[126:129], v[142:145], v[158:161], v[126:129]
	v_mfma_f32_16x16x32_bf16 v[122:125], v[150:153], v[158:161], v[122:125]
	v_mfma_f32_16x16x32_bf16 v[110:113], v[142:145], v[172:175], v[110:113]
	v_mfma_f32_16x16x32_bf16 v[106:109], v[150:153], v[172:175], v[106:109]
	v_mfma_f32_16x16x32_bf16 v[94:97], v[142:145], v[194:197], v[94:97]
	v_mfma_f32_16x16x32_bf16 v[90:93], v[150:153], v[194:197], v[90:93]
	v_mfma_f32_16x16x32_bf16 v[78:81], v[142:145], v[202:205], v[78:81]
	v_mfma_f32_16x16x32_bf16 v[74:77], v[150:153], v[202:205], v[74:77]
	v_mfma_f32_16x16x32_bf16 v[126:129], v[146:149], v[168:171], v[126:129]
	v_mfma_f32_16x16x32_bf16 v[122:125], v[154:157], v[168:171], v[122:125]
	v_mfma_f32_16x16x32_bf16 v[110:113], v[146:149], v[190:193], v[110:113]
	v_mfma_f32_16x16x32_bf16 v[106:109], v[154:157], v[190:193], v[106:109]
	v_mfma_f32_16x16x32_bf16 v[94:97], v[146:149], v[198:201], v[94:97]
	v_mfma_f32_16x16x32_bf16 v[90:93], v[154:157], v[198:201], v[90:93]
	v_mfma_f32_16x16x32_bf16 v[78:81], v[146:149], v[206:209], v[78:81]
	v_mfma_f32_16x16x32_bf16 v[74:77], v[154:157], v[206:209], v[74:77]
	s_barrier
	s_add_i32 s20, 0, 0x1c000
	s_add_i32 s14, s49, s34
	v_add_u32_e32 v167, s20, v164
	s_mov_b32 m0, s14
	ds_read_b128 v[210:213], v167
	ds_read_b128 v[214:217], v167 offset:1024
	ds_read_b128 v[218:221], v167 offset:2048
	ds_read_b128 v[222:225], v167 offset:3072
	global_load_lds_dwordx4 v132, s[64:65]
	s_add_i32 m0, s14, 0x2000
	s_nop 0
	global_load_lds_dwordx4 v136, s[64:65]
	s_barrier
	s_waitcnt lgkmcnt(0)
	s_waitcnt lgkmcnt(0)
	v_mfma_f32_16x16x32_bf16 v[118:121], v[210:213], v[158:161], v[118:121]
	v_mfma_f32_16x16x32_bf16 v[114:117], v[218:221], v[158:161], v[114:117]
	v_mfma_f32_16x16x32_bf16 v[102:105], v[210:213], v[172:175], v[102:105]
	v_mfma_f32_16x16x32_bf16 v[98:101], v[218:221], v[172:175], v[98:101]
	v_mfma_f32_16x16x32_bf16 v[86:89], v[210:213], v[194:197], v[86:89]
	v_mfma_f32_16x16x32_bf16 v[82:85], v[218:221], v[194:197], v[82:85]
	v_mfma_f32_16x16x32_bf16 v[70:73], v[210:213], v[202:205], v[70:73]
	v_mfma_f32_16x16x32_bf16 v[66:69], v[218:221], v[202:205], v[66:69]
	v_mfma_f32_16x16x32_bf16 v[118:121], v[214:217], v[168:171], v[118:121]
	v_mfma_f32_16x16x32_bf16 v[114:117], v[222:225], v[168:171], v[114:117]
	v_mfma_f32_16x16x32_bf16 v[102:105], v[214:217], v[190:193], v[102:105]
	v_mfma_f32_16x16x32_bf16 v[98:101], v[222:225], v[190:193], v[98:101]
	v_mfma_f32_16x16x32_bf16 v[86:89], v[214:217], v[198:201], v[86:89]
	v_mfma_f32_16x16x32_bf16 v[82:85], v[222:225], v[198:201], v[82:85]
	v_mfma_f32_16x16x32_bf16 v[70:73], v[214:217], v[206:209], v[70:73]
	v_mfma_f32_16x16x32_bf16 v[66:69], v[222:225], v[206:209], v[66:69]
	s_barrier
	s_mov_b32 m0, s39
	ds_read_b128 v[158:161], v166 offset:49152
	ds_read_b128 v[168:171], v166 offset:50176
	ds_read_b128 v[172:175], v166 offset:51200
	ds_read_b128 v[190:193], v166 offset:52224
	ds_read_b128 v[194:197], v166 offset:53248
	ds_read_b128 v[198:201], v166 offset:54272
	ds_read_b128 v[202:205], v166 offset:55296
	ds_read_b128 v[206:209], v166 offset:56320
	global_load_lds_dwordx4 v130, s[62:63]
	s_mov_b32 m0, s40
	s_nop 0
	global_load_lds_dwordx4 v134, s[62:63]
	s_barrier
	s_waitcnt lgkmcnt(0)
	s_waitcnt lgkmcnt(0)
	v_mfma_f32_16x16x32_bf16 v[62:65], v[142:145], v[158:161], v[62:65]
	v_mfma_f32_16x16x32_bf16 v[58:61], v[150:153], v[158:161], v[58:61]
	v_mfma_f32_16x16x32_bf16 v[46:49], v[142:145], v[172:175], v[46:49]
	v_mfma_f32_16x16x32_bf16 v[42:45], v[150:153], v[172:175], v[42:45]
	v_mfma_f32_16x16x32_bf16 v[30:33], v[142:145], v[194:197], v[30:33]
	v_mfma_f32_16x16x32_bf16 v[26:29], v[150:153], v[194:197], v[26:29]
	v_mfma_f32_16x16x32_bf16 v[14:17], v[142:145], v[202:205], v[14:17]
	v_mfma_f32_16x16x32_bf16 v[10:13], v[150:153], v[202:205], v[10:13]
	v_mfma_f32_16x16x32_bf16 v[62:65], v[146:149], v[168:171], v[62:65]
	v_mfma_f32_16x16x32_bf16 v[58:61], v[154:157], v[168:171], v[58:61]
	v_mfma_f32_16x16x32_bf16 v[46:49], v[146:149], v[190:193], v[46:49]
	v_mfma_f32_16x16x32_bf16 v[42:45], v[154:157], v[190:193], v[42:45]
	v_mfma_f32_16x16x32_bf16 v[30:33], v[146:149], v[198:201], v[30:33]
	v_mfma_f32_16x16x32_bf16 v[26:29], v[154:157], v[198:201], v[26:29]
	v_mfma_f32_16x16x32_bf16 v[14:17], v[146:149], v[206:209], v[14:17]
	v_mfma_f32_16x16x32_bf16 v[10:13], v[154:157], v[206:209], v[10:13]
	s_barrier
	s_add_u32 s14, s18, 0xb0080
	s_addc_u32 s15, s19, 0
	s_add_i32 s18, s20, s34
	s_mov_b32 m0, s18
	s_nop 0
	global_load_lds_dwordx4 v132, s[14:15]
	s_add_i32 m0, s18, 0x2000
	s_nop 0
	global_load_lds_dwordx4 v136, s[14:15]
	s_waitcnt vmcnt(6)
	s_barrier
	v_mfma_f32_16x16x32_bf16 v[54:57], v[210:213], v[158:161], v[54:57]
	v_mfma_f32_16x16x32_bf16 v[50:53], v[218:221], v[158:161], v[50:53]
	v_mfma_f32_16x16x32_bf16 v[38:41], v[210:213], v[172:175], v[38:41]
	v_mfma_f32_16x16x32_bf16 v[34:37], v[218:221], v[172:175], v[34:37]
	v_mfma_f32_16x16x32_bf16 v[22:25], v[210:213], v[194:197], v[22:25]
	v_mfma_f32_16x16x32_bf16 v[18:21], v[218:221], v[194:197], v[18:21]
	v_mfma_f32_16x16x32_bf16 v[6:9], v[210:213], v[202:205], v[6:9]
	v_mfma_f32_16x16x32_bf16 v[2:5], v[218:221], v[202:205], v[2:5]
	v_mfma_f32_16x16x32_bf16 v[54:57], v[214:217], v[168:171], v[54:57]
	v_mfma_f32_16x16x32_bf16 v[50:53], v[222:225], v[168:171], v[50:53]
	v_mfma_f32_16x16x32_bf16 v[38:41], v[214:217], v[190:193], v[38:41]
	v_mfma_f32_16x16x32_bf16 v[34:37], v[222:225], v[190:193], v[34:37]
	v_mfma_f32_16x16x32_bf16 v[22:25], v[214:217], v[198:201], v[22:25]
	v_mfma_f32_16x16x32_bf16 v[18:21], v[222:225], v[198:201], v[18:21]
	v_mfma_f32_16x16x32_bf16 v[6:9], v[214:217], v[206:209], v[6:9]
	v_mfma_f32_16x16x32_bf16 v[2:5], v[222:225], v[206:209], v[2:5]
	s_barrier
	s_add_i32 s48, s48, 2
	s_add_u32 s46, s46, 0x100
	s_addc_u32 s47, s47, 0
	s_cmp_gt_u32 s48, 41
	s_mov_b64 s[14:15], s[16:17]
	s_cbranch_scc0 .LBB0_374
	s_ashr_i32 s14, s33, 5
	s_mul_hi_i32 s15, s14, 0x9000
	s_mul_i32 s14, s14, 0x9000
	v_lshl_or_b32 v158, s45, 8, v165
	s_add_u32 s14, s26, s14
	s_addc_u32 s15, s27, s15
	v_ashrrev_i32_e32 v159, 31, v158
	v_lshl_add_u64 v[160:161], v[158:159], 2, s[14:15]
	global_load_dwordx4 v[142:145], v[160:161], off offset:16
	global_load_dwordx4 v[146:149], v[160:161], off
	v_lshl_add_u32 v162, s33, 8, v1
	v_ashrrev_i32_e32 v163, 31, v162
	v_lshlrev_b64 v[150:151], 12, v[162:163]
	v_lshl_add_u64 v[150:151], s[12:13], 0, v[150:151]
	v_lshl_add_u64 v[150:151], v[158:159], 1, v[150:151]
	v_mov_b32_e32 v152, 0x10000
	v_mov_b32_e32 v153, 0
	global_load_dwordx4 v[174:177], v[150:151], off offset:2048
	global_load_dwordx4 v[186:189], v[150:151], off offset:2304
	v_lshl_add_u64 v[150:151], v[150:151], 0, v[152:153]
	global_load_dwordx4 v[190:193], v[150:151], off offset:2048
	global_load_dwordx4 v[194:197], v[150:151], off offset:2304
	v_lshl_add_u64 v[150:151], v[150:151], 0, v[152:153]
	global_load_dwordx4 v[198:201], v[150:151], off offset:2048
	global_load_dwordx4 v[202:205], v[150:151], off offset:2304
	v_lshl_add_u64 v[150:151], v[150:151], 0, v[152:153]
	global_load_dwordx4 v[206:209], v[150:151], off offset:2048
	global_load_dwordx4 v[210:213], v[150:151], off offset:2304
	v_mov_b32_e32 v152, 0x50000
	v_lshl_add_u64 v[150:151], v[150:151], 0, v[152:153]
	v_mov_b32_e32 v152, 0x10000
	global_load_dwordx4 v[214:217], v[150:151], off offset:2048
	global_load_dwordx4 v[218:221], v[150:151], off offset:2304
	v_lshl_add_u64 v[150:151], v[150:151], 0, v[152:153]
	global_load_dwordx4 v[222:225], v[150:151], off offset:2048
	global_load_dwordx4 v[226:229], v[150:151], off offset:2304
	v_lshl_add_u64 v[150:151], v[150:151], 0, v[152:153]
	global_load_dwordx4 v[230:233], v[150:151], off offset:2048
	global_load_dwordx4 v[236:239], v[150:151], off offset:2304
	v_lshl_add_u64 v[150:151], v[150:151], 0, v[152:153]
	global_load_dwordx4 v[246:249], v[150:151], off offset:2048
	global_load_dwordx4 v[250:253], v[150:151], off offset:2304
	s_mov_b64 s[14:15], 0x80000
	s_and_b64 vcc, exec, s[4:5]
	s_mov_b32 s45, s43
	s_mov_b32 s33, s44
	s_mov_b64 s[16:17], s[8:9]
	s_waitcnt vmcnt(16)
	v_pk_add_f32 v[144:145], v[144:145], 1.0 op_sel_hi:[1,0]
	v_pk_add_f32 v[148:149], v[148:149], 1.0 op_sel_hi:[1,0]
	v_pk_add_f32 v[146:147], v[146:147], 1.0 op_sel_hi:[1,0]
	v_pk_add_f32 v[142:143], v[142:143], 1.0 op_sel_hi:[1,0]
	v_pk_mul_f32 v[152:153], v[148:149], 0.5 op_sel_hi:[1,0]
	v_pk_mul_f32 v[156:157], v[146:147], 0.5 op_sel_hi:[1,0]
	v_pk_mul_f32 v[150:151], v[144:145], 0.5 op_sel_hi:[1,0]
	v_pk_mul_f32 v[154:155], v[142:143], 0.5 op_sel_hi:[1,0]
	global_load_dwordx4 v[142:145], v[160:161], off offset:528
	global_load_dwordx4 v[146:149], v[160:161], off offset:512
	s_waitcnt vmcnt(0)
	v_pk_add_f32 v[144:145], v[144:145], 1.0 op_sel_hi:[1,0]
	v_pk_add_f32 v[148:149], v[148:149], 1.0 op_sel_hi:[1,0]
	v_pk_add_f32 v[160:161], v[146:147], 1.0 op_sel_hi:[1,0]
	v_pk_mul_f32 v[146:147], v[148:149], 0.5 op_sel_hi:[1,0]
	v_pk_mul_f32 v[148:149], v[160:161], 0.5 op_sel_hi:[1,0]
	v_pk_add_f32 v[160:161], v[142:143], 1.0 op_sel_hi:[1,0]
	v_pk_mul_f32 v[142:143], v[144:145], 0.5 op_sel_hi:[1,0]
	v_pk_mul_f32 v[144:145], v[160:161], 0.5 op_sel_hi:[1,0]
	v_lshlrev_b64 v[160:161], 12, v[162:163]
	v_lshl_add_u64 v[168:169], s[12:13], 0, v[160:161]
	v_lshlrev_b64 v[160:161], 1, v[158:159]
	v_lshl_add_u64 v[158:159], v[168:169], 0, v[160:161]
	v_mov_b32_e32 v168, v174
	v_mov_b32_e32 v169, v175
	v_mov_b32_e32 v170, v176
	v_mov_b32_e32 v171, v177
	s_nop 0
	v_lshlrev_b32_e32 v172, 16, v168
	v_and_b32_e32 v173, 0xffff0000, v168
	v_lshlrev_b32_e32 v168, 16, v169
	v_and_b32_e32 v169, 0xffff0000, v169
	v_pk_fma_f32 v[128:129], v[128:129], v[152:153], v[168:169]
	v_lshlrev_b32_e32 v168, 16, v170
	v_and_b32_e32 v169, 0xffff0000, v170
	v_pk_fma_f32 v[168:169], v[122:123], v[154:155], v[168:169]
	v_lshlrev_b32_e32 v122, 16, v171
	v_and_b32_e32 v123, 0xffff0000, v171
	v_pk_fma_f32 v[126:127], v[126:127], v[156:157], v[172:173]
	v_pk_fma_f32 v[170:171], v[124:125], v[150:151], v[122:123]
	v_cvt_pk_bf16_f32 v122, v126, v127
	v_cvt_pk_bf16_f32 v123, v128, v129
	v_cvt_pk_bf16_f32 v124, v168, v169
	v_cvt_pk_bf16_f32 v125, v170, v171
	global_store_dwordx4 v[158:159], v[122:125], off offset:2048
	s_nop 1
	v_mov_b32_e32 v122, v186
	v_mov_b32_e32 v123, v187
	v_mov_b32_e32 v124, v188
	v_mov_b32_e32 v125, v189
	s_nop 0
	v_lshlrev_b32_e32 v126, 16, v122
	v_and_b32_e32 v127, 0xffff0000, v122
	v_lshlrev_b32_e32 v122, 16, v123
	v_and_b32_e32 v123, 0xffff0000, v123
	v_pk_fma_f32 v[120:121], v[120:121], v[146:147], v[122:123]
	v_lshlrev_b32_e32 v122, 16, v124
	v_and_b32_e32 v123, 0xffff0000, v124
	v_pk_fma_f32 v[122:123], v[114:115], v[144:145], v[122:123]
	v_lshlrev_b32_e32 v114, 16, v125
	v_and_b32_e32 v115, 0xffff0000, v125
	v_pk_fma_f32 v[118:119], v[118:119], v[148:149], v[126:127]
	v_pk_fma_f32 v[124:125], v[116:117], v[142:143], v[114:115]
	v_cvt_pk_bf16_f32 v114, v118, v119
	v_cvt_pk_bf16_f32 v115, v120, v121
	v_cvt_pk_bf16_f32 v116, v122, v123
	v_cvt_pk_bf16_f32 v117, v124, v125
	global_store_dwordx4 v[158:159], v[114:117], off offset:2304
	s_nop 1
	v_or_b32_e32 v114, 16, v162
	v_ashrrev_i32_e32 v115, 31, v114
	v_lshlrev_b64 v[114:115], 12, v[114:115]
	v_lshl_add_u64 v[114:115], s[12:13], 0, v[114:115]
	v_lshl_add_u64 v[118:119], v[114:115], 0, v[160:161]
	v_mov_b32_e32 v114, v190
	v_mov_b32_e32 v115, v191
	v_mov_b32_e32 v116, v192
	v_mov_b32_e32 v117, v193
	s_nop 0
	v_lshlrev_b32_e32 v120, 16, v114
	v_and_b32_e32 v121, 0xffff0000, v114
	v_lshlrev_b32_e32 v114, 16, v115
	v_and_b32_e32 v115, 0xffff0000, v115
	v_pk_fma_f32 v[112:113], v[112:113], v[152:153], v[114:115]
	v_lshlrev_b32_e32 v114, 16, v116
	v_and_b32_e32 v115, 0xffff0000, v116
	v_pk_fma_f32 v[114:115], v[106:107], v[154:155], v[114:115]
	v_lshlrev_b32_e32 v106, 16, v117
	v_and_b32_e32 v107, 0xffff0000, v117
	v_pk_fma_f32 v[110:111], v[110:111], v[156:157], v[120:121]
	v_pk_fma_f32 v[116:117], v[108:109], v[150:151], v[106:107]
	v_cvt_pk_bf16_f32 v106, v110, v111
	v_cvt_pk_bf16_f32 v107, v112, v113
	v_cvt_pk_bf16_f32 v108, v114, v115
	v_cvt_pk_bf16_f32 v109, v116, v117
	global_store_dwordx4 v[118:119], v[106:109], off offset:2048
	s_nop 1
	v_mov_b32_e32 v106, v194
	v_mov_b32_e32 v107, v195
	v_mov_b32_e32 v108, v196
	v_mov_b32_e32 v109, v197
	s_nop 0
	v_lshlrev_b32_e32 v110, 16, v106
	v_and_b32_e32 v111, 0xffff0000, v106
	v_lshlrev_b32_e32 v106, 16, v107
	v_and_b32_e32 v107, 0xffff0000, v107
	v_pk_fma_f32 v[104:105], v[104:105], v[146:147], v[106:107]
	v_lshlrev_b32_e32 v106, 16, v108
	v_and_b32_e32 v107, 0xffff0000, v108
	v_pk_fma_f32 v[106:107], v[98:99], v[144:145], v[106:107]
	v_lshlrev_b32_e32 v98, 16, v109
	v_and_b32_e32 v99, 0xffff0000, v109
	v_pk_fma_f32 v[102:103], v[102:103], v[148:149], v[110:111]
	v_pk_fma_f32 v[108:109], v[100:101], v[142:143], v[98:99]
	v_cvt_pk_bf16_f32 v98, v102, v103
	v_cvt_pk_bf16_f32 v99, v104, v105
	v_cvt_pk_bf16_f32 v100, v106, v107
	v_cvt_pk_bf16_f32 v101, v108, v109
	global_store_dwordx4 v[118:119], v[98:101], off offset:2304
	s_nop 1
	v_or_b32_e32 v98, 32, v162
	v_ashrrev_i32_e32 v99, 31, v98
	v_lshlrev_b64 v[98:99], 12, v[98:99]
	v_lshl_add_u64 v[98:99], s[12:13], 0, v[98:99]
	v_lshl_add_u64 v[102:103], v[98:99], 0, v[160:161]
	v_mov_b32_e32 v98, v198
	v_mov_b32_e32 v99, v199
	v_mov_b32_e32 v100, v200
	v_mov_b32_e32 v101, v201
	s_nop 0
	v_lshlrev_b32_e32 v104, 16, v98
	v_and_b32_e32 v105, 0xffff0000, v98
	v_lshlrev_b32_e32 v98, 16, v99
	v_and_b32_e32 v99, 0xffff0000, v99
	v_pk_fma_f32 v[96:97], v[96:97], v[152:153], v[98:99]
	v_lshlrev_b32_e32 v98, 16, v100
	v_and_b32_e32 v99, 0xffff0000, v100
	v_pk_fma_f32 v[98:99], v[90:91], v[154:155], v[98:99]
	v_lshlrev_b32_e32 v90, 16, v101
	v_and_b32_e32 v91, 0xffff0000, v101
	v_pk_fma_f32 v[94:95], v[94:95], v[156:157], v[104:105]
	v_pk_fma_f32 v[100:101], v[92:93], v[150:151], v[90:91]
	v_cvt_pk_bf16_f32 v90, v94, v95
	v_cvt_pk_bf16_f32 v91, v96, v97
	v_cvt_pk_bf16_f32 v92, v98, v99
	v_cvt_pk_bf16_f32 v93, v100, v101
	global_store_dwordx4 v[102:103], v[90:93], off offset:2048
	s_nop 1
	v_mov_b32_e32 v90, v202
	v_mov_b32_e32 v91, v203
	v_mov_b32_e32 v92, v204
	v_mov_b32_e32 v93, v205
	s_nop 0
	v_lshlrev_b32_e32 v94, 16, v90
	v_and_b32_e32 v95, 0xffff0000, v90
	v_lshlrev_b32_e32 v90, 16, v91
	v_and_b32_e32 v91, 0xffff0000, v91
	v_pk_fma_f32 v[88:89], v[88:89], v[146:147], v[90:91]
	v_lshlrev_b32_e32 v90, 16, v92
	v_and_b32_e32 v91, 0xffff0000, v92
	v_pk_fma_f32 v[90:91], v[82:83], v[144:145], v[90:91]
	v_lshlrev_b32_e32 v82, 16, v93
	v_and_b32_e32 v83, 0xffff0000, v93
	v_pk_fma_f32 v[86:87], v[86:87], v[148:149], v[94:95]
	v_pk_fma_f32 v[92:93], v[84:85], v[142:143], v[82:83]
	v_cvt_pk_bf16_f32 v82, v86, v87
	v_cvt_pk_bf16_f32 v83, v88, v89
	v_cvt_pk_bf16_f32 v84, v90, v91
	v_cvt_pk_bf16_f32 v85, v92, v93
	global_store_dwordx4 v[102:103], v[82:85], off offset:2304
	s_nop 1
	v_or_b32_e32 v82, 48, v162
	v_ashrrev_i32_e32 v83, 31, v82
	v_lshlrev_b64 v[82:83], 12, v[82:83]
	v_lshl_add_u64 v[82:83], s[12:13], 0, v[82:83]
	v_lshl_add_u64 v[82:83], v[82:83], 0, v[160:161]
	v_mov_b32_e32 v84, v206
	v_mov_b32_e32 v85, v207
	v_mov_b32_e32 v86, v208
	v_mov_b32_e32 v87, v209
	s_nop 0
	v_lshlrev_b32_e32 v88, 16, v84
	v_and_b32_e32 v89, 0xffff0000, v84
	v_lshlrev_b32_e32 v84, 16, v85
	v_and_b32_e32 v85, 0xffff0000, v85
	v_pk_fma_f32 v[80:81], v[80:81], v[152:153], v[84:85]
	v_lshlrev_b32_e32 v84, 16, v86
	v_and_b32_e32 v85, 0xffff0000, v86
	v_pk_fma_f32 v[84:85], v[74:75], v[154:155], v[84:85]
	v_lshlrev_b32_e32 v74, 16, v87
	v_and_b32_e32 v75, 0xffff0000, v87
	v_pk_fma_f32 v[78:79], v[78:79], v[156:157], v[88:89]
	v_pk_fma_f32 v[86:87], v[76:77], v[150:151], v[74:75]
	v_cvt_pk_bf16_f32 v74, v78, v79
	v_cvt_pk_bf16_f32 v75, v80, v81
	v_cvt_pk_bf16_f32 v76, v84, v85
	v_cvt_pk_bf16_f32 v77, v86, v87
	global_store_dwordx4 v[82:83], v[74:77], off offset:2048
	s_nop 1
	v_mov_b32_e32 v74, v210
	v_mov_b32_e32 v75, v211
	v_mov_b32_e32 v76, v212
	v_mov_b32_e32 v77, v213
	s_nop 0
	v_lshlrev_b32_e32 v78, 16, v74
	v_and_b32_e32 v79, 0xffff0000, v74
	v_lshlrev_b32_e32 v74, 16, v75
	v_and_b32_e32 v75, 0xffff0000, v75
	v_pk_fma_f32 v[72:73], v[72:73], v[146:147], v[74:75]
	v_lshlrev_b32_e32 v74, 16, v76
	v_and_b32_e32 v75, 0xffff0000, v76
	v_pk_fma_f32 v[74:75], v[66:67], v[144:145], v[74:75]
	v_lshlrev_b32_e32 v66, 16, v77
	v_and_b32_e32 v67, 0xffff0000, v77
	v_pk_fma_f32 v[70:71], v[70:71], v[148:149], v[78:79]
	v_pk_fma_f32 v[76:77], v[68:69], v[142:143], v[66:67]
	v_cvt_pk_bf16_f32 v66, v70, v71
	v_cvt_pk_bf16_f32 v67, v72, v73
	v_cvt_pk_bf16_f32 v68, v74, v75
	v_cvt_pk_bf16_f32 v69, v76, v77
	v_lshl_add_u64 v[70:71], v[158:159], 0, s[14:15]
	global_store_dwordx4 v[82:83], v[66:69], off offset:2304
	s_nop 1
	v_mov_b32_e32 v66, v214
	v_mov_b32_e32 v67, v215
	v_mov_b32_e32 v68, v216
	v_mov_b32_e32 v69, v217
	s_mov_b64 s[14:15], 0x90000
	s_nop 0
	v_lshlrev_b32_e32 v72, 16, v66
	v_and_b32_e32 v73, 0xffff0000, v66
	v_lshlrev_b32_e32 v66, 16, v67
	v_and_b32_e32 v67, 0xffff0000, v67
	v_pk_fma_f32 v[64:65], v[64:65], v[152:153], v[66:67]
	v_lshlrev_b32_e32 v66, 16, v68
	v_and_b32_e32 v67, 0xffff0000, v68
	v_pk_fma_f32 v[66:67], v[58:59], v[154:155], v[66:67]
	v_lshlrev_b32_e32 v58, 16, v69
	v_and_b32_e32 v59, 0xffff0000, v69
	v_pk_fma_f32 v[62:63], v[62:63], v[156:157], v[72:73]
	v_pk_fma_f32 v[68:69], v[60:61], v[150:151], v[58:59]
	v_cvt_pk_bf16_f32 v58, v62, v63
	v_cvt_pk_bf16_f32 v59, v64, v65
	v_cvt_pk_bf16_f32 v60, v66, v67
	v_cvt_pk_bf16_f32 v61, v68, v69
	global_store_dwordx4 v[70:71], v[58:61], off offset:2048
	s_nop 1
	v_mov_b32_e32 v58, v218
	v_mov_b32_e32 v59, v219
	v_mov_b32_e32 v60, v220
	v_mov_b32_e32 v61, v221
	s_nop 0
	v_lshlrev_b32_e32 v62, 16, v58
	v_and_b32_e32 v63, 0xffff0000, v58
	v_lshlrev_b32_e32 v58, 16, v59
	v_and_b32_e32 v59, 0xffff0000, v59
	v_pk_fma_f32 v[56:57], v[56:57], v[146:147], v[58:59]
	v_lshlrev_b32_e32 v58, 16, v60
	v_and_b32_e32 v59, 0xffff0000, v60
	v_pk_fma_f32 v[58:59], v[50:51], v[144:145], v[58:59]
	v_lshlrev_b32_e32 v50, 16, v61
	v_and_b32_e32 v51, 0xffff0000, v61
	v_pk_fma_f32 v[54:55], v[54:55], v[148:149], v[62:63]
	v_pk_fma_f32 v[60:61], v[52:53], v[142:143], v[50:51]
	v_cvt_pk_bf16_f32 v50, v54, v55
	v_cvt_pk_bf16_f32 v51, v56, v57
	v_cvt_pk_bf16_f32 v52, v58, v59
	v_cvt_pk_bf16_f32 v53, v60, v61
	v_lshl_add_u64 v[54:55], v[158:159], 0, s[14:15]
	global_store_dwordx4 v[70:71], v[50:53], off offset:2304
	s_nop 1
	v_mov_b32_e32 v50, v222
	v_mov_b32_e32 v51, v223
	v_mov_b32_e32 v52, v224
	v_mov_b32_e32 v53, v225
	s_mov_b64 s[14:15], 0xa0000
	s_nop 0
	v_lshlrev_b32_e32 v56, 16, v50
	v_and_b32_e32 v57, 0xffff0000, v50
	v_lshlrev_b32_e32 v50, 16, v51
	v_and_b32_e32 v51, 0xffff0000, v51
	v_pk_fma_f32 v[48:49], v[48:49], v[152:153], v[50:51]
	v_lshlrev_b32_e32 v50, 16, v52
	v_and_b32_e32 v51, 0xffff0000, v52
	v_pk_fma_f32 v[50:51], v[42:43], v[154:155], v[50:51]
	v_lshlrev_b32_e32 v42, 16, v53
	v_and_b32_e32 v43, 0xffff0000, v53
	v_pk_fma_f32 v[46:47], v[46:47], v[156:157], v[56:57]
	v_pk_fma_f32 v[52:53], v[44:45], v[150:151], v[42:43]
	v_cvt_pk_bf16_f32 v42, v46, v47
	v_cvt_pk_bf16_f32 v43, v48, v49
	v_cvt_pk_bf16_f32 v44, v50, v51
	v_cvt_pk_bf16_f32 v45, v52, v53
	global_store_dwordx4 v[54:55], v[42:45], off offset:2048
	s_nop 1
	v_mov_b32_e32 v42, v226
	v_mov_b32_e32 v43, v227
	v_mov_b32_e32 v44, v228
	v_mov_b32_e32 v45, v229
	s_nop 0
	v_lshlrev_b32_e32 v46, 16, v42
	v_and_b32_e32 v47, 0xffff0000, v42
	v_lshlrev_b32_e32 v42, 16, v43
	v_and_b32_e32 v43, 0xffff0000, v43
	v_pk_fma_f32 v[40:41], v[40:41], v[146:147], v[42:43]
	v_lshlrev_b32_e32 v42, 16, v44
	v_and_b32_e32 v43, 0xffff0000, v44
	v_pk_fma_f32 v[42:43], v[34:35], v[144:145], v[42:43]
	v_lshlrev_b32_e32 v34, 16, v45
	v_and_b32_e32 v35, 0xffff0000, v45
	v_pk_fma_f32 v[38:39], v[38:39], v[148:149], v[46:47]
	v_pk_fma_f32 v[44:45], v[36:37], v[142:143], v[34:35]
	v_cvt_pk_bf16_f32 v34, v38, v39
	v_cvt_pk_bf16_f32 v35, v40, v41
	v_cvt_pk_bf16_f32 v36, v42, v43
	v_cvt_pk_bf16_f32 v37, v44, v45
	v_lshl_add_u64 v[38:39], v[158:159], 0, s[14:15]
	global_store_dwordx4 v[54:55], v[34:37], off offset:2304
	s_nop 1
	v_mov_b32_e32 v34, v230
	v_mov_b32_e32 v35, v231
	v_mov_b32_e32 v36, v232
	v_mov_b32_e32 v37, v233
	s_mov_b64 s[14:15], 0xb0000
	s_nop 0
	v_lshlrev_b32_e32 v40, 16, v34
	v_and_b32_e32 v41, 0xffff0000, v34
	v_lshlrev_b32_e32 v34, 16, v35
	v_and_b32_e32 v35, 0xffff0000, v35
	v_pk_fma_f32 v[32:33], v[32:33], v[152:153], v[34:35]
	v_lshlrev_b32_e32 v34, 16, v36
	v_and_b32_e32 v35, 0xffff0000, v36
	v_pk_fma_f32 v[34:35], v[26:27], v[154:155], v[34:35]
	v_lshlrev_b32_e32 v26, 16, v37
	v_and_b32_e32 v27, 0xffff0000, v37
	v_pk_fma_f32 v[30:31], v[30:31], v[156:157], v[40:41]
	v_pk_fma_f32 v[36:37], v[28:29], v[150:151], v[26:27]
	v_cvt_pk_bf16_f32 v26, v30, v31
	v_cvt_pk_bf16_f32 v27, v32, v33
	v_cvt_pk_bf16_f32 v28, v34, v35
	v_cvt_pk_bf16_f32 v29, v36, v37
	global_store_dwordx4 v[38:39], v[26:29], off offset:2048
	s_nop 1
	v_mov_b32_e32 v26, v236
	v_mov_b32_e32 v27, v237
	v_mov_b32_e32 v28, v238
	v_mov_b32_e32 v29, v239
	s_nop 0
	v_lshlrev_b32_e32 v30, 16, v26
	v_and_b32_e32 v31, 0xffff0000, v26
	v_lshlrev_b32_e32 v26, 16, v27
	v_and_b32_e32 v27, 0xffff0000, v27
	v_pk_fma_f32 v[24:25], v[24:25], v[146:147], v[26:27]
	v_lshlrev_b32_e32 v26, 16, v28
	v_and_b32_e32 v27, 0xffff0000, v28
	v_pk_fma_f32 v[26:27], v[18:19], v[144:145], v[26:27]
	v_lshlrev_b32_e32 v18, 16, v29
	v_and_b32_e32 v19, 0xffff0000, v29
	v_pk_fma_f32 v[22:23], v[22:23], v[148:149], v[30:31]
	v_pk_fma_f32 v[28:29], v[20:21], v[142:143], v[18:19]
	v_cvt_pk_bf16_f32 v18, v22, v23
	v_cvt_pk_bf16_f32 v19, v24, v25
	v_cvt_pk_bf16_f32 v20, v26, v27
	v_cvt_pk_bf16_f32 v21, v28, v29
	global_store_dwordx4 v[38:39], v[18:21], off offset:2304
	s_nop 1
	v_lshl_add_u64 v[18:19], v[158:159], 0, s[14:15]
	v_mov_b32_e32 v20, v246
	v_mov_b32_e32 v21, v247
	v_mov_b32_e32 v22, v248
	v_mov_b32_e32 v23, v249
	s_mov_b64 s[14:15], s[6:7]
	s_nop 0
	v_lshlrev_b32_e32 v24, 16, v20
	v_and_b32_e32 v25, 0xffff0000, v20
	v_lshlrev_b32_e32 v20, 16, v21
	v_and_b32_e32 v21, 0xffff0000, v21
	v_pk_fma_f32 v[16:17], v[16:17], v[152:153], v[20:21]
	v_lshlrev_b32_e32 v20, 16, v22
	v_and_b32_e32 v21, 0xffff0000, v22
	v_pk_fma_f32 v[20:21], v[10:11], v[154:155], v[20:21]
	v_lshlrev_b32_e32 v10, 16, v23
	v_and_b32_e32 v11, 0xffff0000, v23
	v_pk_fma_f32 v[14:15], v[14:15], v[156:157], v[24:25]
	v_pk_fma_f32 v[22:23], v[12:13], v[150:151], v[10:11]
	v_cvt_pk_bf16_f32 v10, v14, v15
	v_cvt_pk_bf16_f32 v11, v16, v17
	v_cvt_pk_bf16_f32 v12, v20, v21
	v_cvt_pk_bf16_f32 v13, v22, v23
	global_store_dwordx4 v[18:19], v[10:13], off offset:2048
	s_nop 1
	v_mov_b32_e32 v10, v250
	v_mov_b32_e32 v11, v251
	v_mov_b32_e32 v12, v252
	v_mov_b32_e32 v13, v253
	s_nop 0
	v_lshlrev_b32_e32 v14, 16, v10
	v_and_b32_e32 v15, 0xffff0000, v10
	v_lshlrev_b32_e32 v10, 16, v11
	v_and_b32_e32 v11, 0xffff0000, v11
	v_pk_fma_f32 v[8:9], v[8:9], v[146:147], v[10:11]
	v_lshlrev_b32_e32 v10, 16, v12
	v_and_b32_e32 v11, 0xffff0000, v12
	v_pk_fma_f32 v[10:11], v[2:3], v[144:145], v[10:11]
	v_lshlrev_b32_e32 v2, 16, v13
	v_and_b32_e32 v3, 0xffff0000, v13
	v_pk_fma_f32 v[6:7], v[6:7], v[148:149], v[14:15]
	v_pk_fma_f32 v[12:13], v[4:5], v[142:143], v[2:3]
	v_cvt_pk_bf16_f32 v2, v6, v7
	v_cvt_pk_bf16_f32 v3, v8, v9
	v_cvt_pk_bf16_f32 v4, v10, v11
	v_cvt_pk_bf16_f32 v5, v12, v13
	global_store_dwordx4 v[18:19], v[2:5], off offset:2304
	s_cbranch_vccz .LBB0_363
	s_waitcnt vmcnt(0)
	s_cmpk_gt_u32 s30, 0xff
	s_cbranch_scc1 .LBB0_378
	s_barrier

.LBB0_400:
	s_add_u32 s16, s14, 0x100
	s_addc_u32 s17, s15, 0
	s_add_i32 s49, 0, 0x10000
	v_add_u32_e32 v154, s49, v164
	ds_read_b128 v[142:145], v154
	ds_read_b128 v[146:149], v154 offset:1024
	ds_read_b128 v[150:153], v154 offset:2048
	ds_read_b128 v[154:157], v154 offset:3072
	s_cmp_eq_u32 s48, 40
	s_cselect_b32 s21, s7, s17
	s_cselect_b32 s20, s6, s16
	s_cselect_b32 s19, s9, s47
	s_cselect_b32 s18, s8, s46
	v_lshl_add_u64 v[162:163], s[14:15], 0, v[138:139]
	s_add_i32 m0, s34, 0xc000
	ds_read_b128 v[158:161], v166
	ds_read_b128 v[168:171], v166 offset:1024
	ds_read_b128 v[172:175], v166 offset:2048
	ds_read_b128 v[190:193], v166 offset:3072
	ds_read_b128 v[194:197], v166 offset:4096
	ds_read_b128 v[198:201], v166 offset:5120
	ds_read_b128 v[202:205], v166 offset:6144
	ds_read_b128 v[206:209], v166 offset:7168
	global_load_lds_dwordx4 v[162:163], off
	v_lshl_add_u64 v[162:163], s[14:15], 0, v[140:141]
	s_add_i32 m0, s34, 0xe000
	s_nop 0
	global_load_lds_dwordx4 v[162:163], off
	s_waitcnt lgkmcnt(8)
	s_barrier
	s_waitcnt lgkmcnt(0)
	s_waitcnt lgkmcnt(0)
	v_mfma_f32_16x16x32_bf16 v[126:129], v[142:145], v[158:161], v[126:129]
	v_mfma_f32_16x16x32_bf16 v[122:125], v[150:153], v[158:161], v[122:125]
	v_mfma_f32_16x16x32_bf16 v[110:113], v[142:145], v[172:175], v[110:113]
	v_mfma_f32_16x16x32_bf16 v[106:109], v[150:153], v[172:175], v[106:109]
	v_mfma_f32_16x16x32_bf16 v[94:97], v[142:145], v[194:197], v[94:97]
	v_mfma_f32_16x16x32_bf16 v[90:93], v[150:153], v[194:197], v[90:93]
	v_mfma_f32_16x16x32_bf16 v[78:81], v[142:145], v[202:205], v[78:81]
	v_mfma_f32_16x16x32_bf16 v[74:77], v[150:153], v[202:205], v[74:77]
	v_mfma_f32_16x16x32_bf16 v[126:129], v[146:149], v[168:171], v[126:129]
	v_mfma_f32_16x16x32_bf16 v[122:125], v[154:157], v[168:171], v[122:125]
	v_mfma_f32_16x16x32_bf16 v[110:113], v[146:149], v[190:193], v[110:113]
	v_mfma_f32_16x16x32_bf16 v[106:109], v[154:157], v[190:193], v[106:109]
	v_mfma_f32_16x16x32_bf16 v[94:97], v[146:149], v[198:201], v[94:97]
	v_mfma_f32_16x16x32_bf16 v[90:93], v[154:157], v[198:201], v[90:93]
	v_mfma_f32_16x16x32_bf16 v[78:81], v[146:149], v[206:209], v[78:81]
	v_mfma_f32_16x16x32_bf16 v[74:77], v[154:157], v[206:209], v[74:77]
	s_barrier
	s_add_i32 s50, 0, 0x14000
	v_add_u32_e32 v162, s50, v164
	s_add_i32 s14, s49, s33
	ds_read_b128 v[210:213], v162
	ds_read_b128 v[214:217], v162 offset:1024
	ds_read_b128 v[218:221], v162 offset:2048
	ds_read_b128 v[222:225], v162 offset:3072
	s_add_u32 s64, s18, 0x80
	s_addc_u32 s65, s19, 0
	s_mov_b32 m0, s14
	s_nop 0
	global_load_lds_dwordx4 v132, s[18:19]
	s_add_i32 m0, s14, 0x2000
	s_nop 0
	global_load_lds_dwordx4 v136, s[18:19]
	s_barrier
	s_waitcnt lgkmcnt(0)
	s_waitcnt lgkmcnt(0)
	v_mfma_f32_16x16x32_bf16 v[118:121], v[210:213], v[158:161], v[118:121]
	v_mfma_f32_16x16x32_bf16 v[114:117], v[218:221], v[158:161], v[114:117]
	v_mfma_f32_16x16x32_bf16 v[102:105], v[210:213], v[172:175], v[102:105]
	v_mfma_f32_16x16x32_bf16 v[98:101], v[218:221], v[172:175], v[98:101]
	v_mfma_f32_16x16x32_bf16 v[86:89], v[210:213], v[194:197], v[86:89]
	v_mfma_f32_16x16x32_bf16 v[82:85], v[218:221], v[194:197], v[82:85]
	v_mfma_f32_16x16x32_bf16 v[70:73], v[210:213], v[202:205], v[70:73]
	v_mfma_f32_16x16x32_bf16 v[66:69], v[218:221], v[202:205], v[66:69]
	v_mfma_f32_16x16x32_bf16 v[118:121], v[214:217], v[168:171], v[118:121]
	v_mfma_f32_16x16x32_bf16 v[114:117], v[222:225], v[168:171], v[114:117]
	v_mfma_f32_16x16x32_bf16 v[102:105], v[214:217], v[190:193], v[102:105]
	v_mfma_f32_16x16x32_bf16 v[98:101], v[222:225], v[190:193], v[98:101]
	v_mfma_f32_16x16x32_bf16 v[86:89], v[214:217], v[198:201], v[86:89]
	v_mfma_f32_16x16x32_bf16 v[82:85], v[222:225], v[198:201], v[82:85]
	v_mfma_f32_16x16x32_bf16 v[70:73], v[214:217], v[206:209], v[70:73]
	v_mfma_f32_16x16x32_bf16 v[66:69], v[222:225], v[206:209], v[66:69]
	s_barrier
	s_mov_b32 m0, s34
	s_add_u32 s62, s20, 0x80
	s_addc_u32 s63, s21, 0
	ds_read_b128 v[158:161], v166 offset:16384
	ds_read_b128 v[168:171], v166 offset:17408
	ds_read_b128 v[172:175], v166 offset:18432
	ds_read_b128 v[190:193], v166 offset:19456
	ds_read_b128 v[194:197], v166 offset:20480
	ds_read_b128 v[198:201], v166 offset:21504
	ds_read_b128 v[202:205], v166 offset:22528
	ds_read_b128 v[206:209], v166 offset:23552
	global_load_lds_dwordx4 v130, s[20:21]
	s_mov_b32 m0, s35
	s_nop 0
	global_load_lds_dwordx4 v134, s[20:21]
	s_barrier
	s_waitcnt lgkmcnt(0)
	s_waitcnt lgkmcnt(0)
	v_mfma_f32_16x16x32_bf16 v[62:65], v[142:145], v[158:161], v[62:65]
	v_mfma_f32_16x16x32_bf16 v[58:61], v[150:153], v[158:161], v[58:61]
	v_mfma_f32_16x16x32_bf16 v[46:49], v[142:145], v[172:175], v[46:49]
	v_mfma_f32_16x16x32_bf16 v[42:45], v[150:153], v[172:175], v[42:45]
	v_mfma_f32_16x16x32_bf16 v[30:33], v[142:145], v[194:197], v[30:33]
	v_mfma_f32_16x16x32_bf16 v[26:29], v[150:153], v[194:197], v[26:29]
	v_mfma_f32_16x16x32_bf16 v[14:17], v[142:145], v[202:205], v[14:17]
	v_mfma_f32_16x16x32_bf16 v[10:13], v[150:153], v[202:205], v[10:13]
	v_mfma_f32_16x16x32_bf16 v[62:65], v[146:149], v[168:171], v[62:65]
	v_mfma_f32_16x16x32_bf16 v[58:61], v[154:157], v[168:171], v[58:61]
	v_mfma_f32_16x16x32_bf16 v[46:49], v[146:149], v[190:193], v[46:49]
	v_mfma_f32_16x16x32_bf16 v[42:45], v[154:157], v[190:193], v[42:45]
	v_mfma_f32_16x16x32_bf16 v[30:33], v[146:149], v[198:201], v[30:33]
	v_mfma_f32_16x16x32_bf16 v[26:29], v[154:157], v[198:201], v[26:29]
	v_mfma_f32_16x16x32_bf16 v[14:17], v[146:149], v[206:209], v[14:17]
	v_mfma_f32_16x16x32_bf16 v[10:13], v[154:157], v[206:209], v[10:13]
	s_barrier
	s_add_u32 s14, s18, 0xb0000
	s_addc_u32 s15, s19, 0
	s_add_i32 s49, s50, s33
	s_mov_b32 m0, s49
	s_nop 0
	global_load_lds_dwordx4 v132, s[14:15]
	s_add_i32 m0, s49, 0x2000
	s_nop 0
	global_load_lds_dwordx4 v136, s[14:15]
	s_waitcnt vmcnt(6)
	s_barrier
	v_mfma_f32_16x16x32_bf16 v[54:57], v[210:213], v[158:161], v[54:57]
	v_mfma_f32_16x16x32_bf16 v[50:53], v[218:221], v[158:161], v[50:53]
	v_mfma_f32_16x16x32_bf16 v[38:41], v[210:213], v[172:175], v[38:41]
	v_mfma_f32_16x16x32_bf16 v[34:37], v[218:221], v[172:175], v[34:37]
	v_mfma_f32_16x16x32_bf16 v[22:25], v[210:213], v[194:197], v[22:25]
	v_mfma_f32_16x16x32_bf16 v[18:21], v[218:221], v[194:197], v[18:21]
	v_mfma_f32_16x16x32_bf16 v[6:9], v[210:213], v[202:205], v[6:9]
	v_mfma_f32_16x16x32_bf16 v[2:5], v[218:221], v[202:205], v[2:5]
	v_mfma_f32_16x16x32_bf16 v[54:57], v[214:217], v[168:171], v[54:57]
	v_mfma_f32_16x16x32_bf16 v[50:53], v[222:225], v[168:171], v[50:53]
	v_mfma_f32_16x16x32_bf16 v[38:41], v[214:217], v[190:193], v[38:41]
	v_mfma_f32_16x16x32_bf16 v[34:37], v[222:225], v[190:193], v[34:37]
	v_mfma_f32_16x16x32_bf16 v[22:25], v[214:217], v[198:201], v[22:25]
	v_mfma_f32_16x16x32_bf16 v[18:21], v[222:225], v[198:201], v[18:21]
	v_mfma_f32_16x16x32_bf16 v[6:9], v[214:217], v[206:209], v[6:9]
	v_mfma_f32_16x16x32_bf16 v[2:5], v[222:225], v[206:209], v[2:5]
	s_barrier
	s_add_i32 s49, 0, 0x18000
	v_add_u32_e32 v154, s49, v164
	ds_read_b128 v[142:145], v154
	ds_read_b128 v[146:149], v154 offset:1024
	ds_read_b128 v[150:153], v154 offset:2048
	ds_read_b128 v[154:157], v154 offset:3072
	s_add_u32 s14, s20, 0xb8000
	s_addc_u32 s15, s21, 0
	s_mov_b32 m0, s36
	ds_read_b128 v[158:161], v166 offset:32768
	ds_read_b128 v[168:171], v166 offset:33792
	ds_read_b128 v[172:175], v166 offset:34816
	ds_read_b128 v[190:193], v166 offset:35840
	ds_read_b128 v[194:197], v166 offset:36864
	ds_read_b128 v[198:201], v166 offset:37888
	ds_read_b128 v[202:205], v166 offset:38912
	ds_read_b128 v[206:209], v166 offset:39936
	global_load_lds_dwordx4 v130, s[14:15]
	s_mov_b32 m0, s37
	s_nop 0
	global_load_lds_dwordx4 v134, s[14:15]
	s_waitcnt lgkmcnt(8)
	s_barrier
	s_waitcnt lgkmcnt(0)
	s_waitcnt lgkmcnt(0)
	v_mfma_f32_16x16x32_bf16 v[126:129], v[142:145], v[158:161], v[126:129]
	v_mfma_f32_16x16x32_bf16 v[122:125], v[150:153], v[158:161], v[122:125]
	v_mfma_f32_16x16x32_bf16 v[110:113], v[142:145], v[172:175], v[110:113]
	v_mfma_f32_16x16x32_bf16 v[106:109], v[150:153], v[172:175], v[106:109]
	v_mfma_f32_16x16x32_bf16 v[94:97], v[142:145], v[194:197], v[94:97]
	v_mfma_f32_16x16x32_bf16 v[90:93], v[150:153], v[194:197], v[90:93]
	v_mfma_f32_16x16x32_bf16 v[78:81], v[142:145], v[202:205], v[78:81]
	v_mfma_f32_16x16x32_bf16 v[74:77], v[150:153], v[202:205], v[74:77]
	v_mfma_f32_16x16x32_bf16 v[126:129], v[146:149], v[168:171], v[126:129]
	v_mfma_f32_16x16x32_bf16 v[122:125], v[154:157], v[168:171], v[122:125]
	v_mfma_f32_16x16x32_bf16 v[110:113], v[146:149], v[190:193], v[110:113]
	v_mfma_f32_16x16x32_bf16 v[106:109], v[154:157], v[190:193], v[106:109]
	v_mfma_f32_16x16x32_bf16 v[94:97], v[146:149], v[198:201], v[94:97]
	v_mfma_f32_16x16x32_bf16 v[90:93], v[154:157], v[198:201], v[90:93]
	v_mfma_f32_16x16x32_bf16 v[78:81], v[146:149], v[206:209], v[78:81]
	v_mfma_f32_16x16x32_bf16 v[74:77], v[154:157], v[206:209], v[74:77]
	s_barrier
	s_add_i32 s20, 0, 0x1c000
	s_add_i32 s14, s49, s33
	v_add_u32_e32 v167, s20, v164
	s_mov_b32 m0, s14
	ds_read_b128 v[210:213], v167
	ds_read_b128 v[214:217], v167 offset:1024
	ds_read_b128 v[218:221], v167 offset:2048
	ds_read_b128 v[222:225], v167 offset:3072
	global_load_lds_dwordx4 v132, s[64:65]
	s_add_i32 m0, s14, 0x2000
	s_nop 0
	global_load_lds_dwordx4 v136, s[64:65]
	s_barrier
	s_waitcnt lgkmcnt(0)
	s_waitcnt lgkmcnt(0)
	v_mfma_f32_16x16x32_bf16 v[118:121], v[210:213], v[158:161], v[118:121]
	v_mfma_f32_16x16x32_bf16 v[114:117], v[218:221], v[158:161], v[114:117]
	v_mfma_f32_16x16x32_bf16 v[102:105], v[210:213], v[172:175], v[102:105]
	v_mfma_f32_16x16x32_bf16 v[98:101], v[218:221], v[172:175], v[98:101]
	v_mfma_f32_16x16x32_bf16 v[86:89], v[210:213], v[194:197], v[86:89]
	v_mfma_f32_16x16x32_bf16 v[82:85], v[218:221], v[194:197], v[82:85]
	v_mfma_f32_16x16x32_bf16 v[70:73], v[210:213], v[202:205], v[70:73]
	v_mfma_f32_16x16x32_bf16 v[66:69], v[218:221], v[202:205], v[66:69]
	v_mfma_f32_16x16x32_bf16 v[118:121], v[214:217], v[168:171], v[118:121]
	v_mfma_f32_16x16x32_bf16 v[114:117], v[222:225], v[168:171], v[114:117]
	v_mfma_f32_16x16x32_bf16 v[102:105], v[214:217], v[190:193], v[102:105]
	v_mfma_f32_16x16x32_bf16 v[98:101], v[222:225], v[190:193], v[98:101]
	v_mfma_f32_16x16x32_bf16 v[86:89], v[214:217], v[198:201], v[86:89]
	v_mfma_f32_16x16x32_bf16 v[82:85], v[222:225], v[198:201], v[82:85]
	v_mfma_f32_16x16x32_bf16 v[70:73], v[214:217], v[206:209], v[70:73]
	v_mfma_f32_16x16x32_bf16 v[66:69], v[222:225], v[206:209], v[66:69]
	s_barrier
	s_mov_b32 m0, s38
	ds_read_b128 v[158:161], v166 offset:49152
	ds_read_b128 v[168:171], v166 offset:50176
	ds_read_b128 v[172:175], v166 offset:51200
	ds_read_b128 v[190:193], v166 offset:52224
	ds_read_b128 v[194:197], v166 offset:53248
	ds_read_b128 v[198:201], v166 offset:54272
	ds_read_b128 v[202:205], v166 offset:55296
	ds_read_b128 v[206:209], v166 offset:56320
	global_load_lds_dwordx4 v130, s[62:63]
	s_mov_b32 m0, s39
	s_nop 0
	global_load_lds_dwordx4 v134, s[62:63]
	s_barrier
	s_waitcnt lgkmcnt(0)
	s_waitcnt lgkmcnt(0)
	v_mfma_f32_16x16x32_bf16 v[62:65], v[142:145], v[158:161], v[62:65]
	v_mfma_f32_16x16x32_bf16 v[58:61], v[150:153], v[158:161], v[58:61]
	v_mfma_f32_16x16x32_bf16 v[46:49], v[142:145], v[172:175], v[46:49]
	v_mfma_f32_16x16x32_bf16 v[42:45], v[150:153], v[172:175], v[42:45]
	v_mfma_f32_16x16x32_bf16 v[30:33], v[142:145], v[194:197], v[30:33]
	v_mfma_f32_16x16x32_bf16 v[26:29], v[150:153], v[194:197], v[26:29]
	v_mfma_f32_16x16x32_bf16 v[14:17], v[142:145], v[202:205], v[14:17]
	v_mfma_f32_16x16x32_bf16 v[10:13], v[150:153], v[202:205], v[10:13]
	v_mfma_f32_16x16x32_bf16 v[62:65], v[146:149], v[168:171], v[62:65]
	v_mfma_f32_16x16x32_bf16 v[58:61], v[154:157], v[168:171], v[58:61]
	v_mfma_f32_16x16x32_bf16 v[46:49], v[146:149], v[190:193], v[46:49]
	v_mfma_f32_16x16x32_bf16 v[42:45], v[154:157], v[190:193], v[42:45]
	v_mfma_f32_16x16x32_bf16 v[30:33], v[146:149], v[198:201], v[30:33]
	v_mfma_f32_16x16x32_bf16 v[26:29], v[154:157], v[198:201], v[26:29]
	v_mfma_f32_16x16x32_bf16 v[14:17], v[146:149], v[206:209], v[14:17]
	v_mfma_f32_16x16x32_bf16 v[10:13], v[154:157], v[206:209], v[10:13]
	s_barrier
	s_add_u32 s14, s18, 0xb0080
	s_addc_u32 s15, s19, 0
	s_add_i32 s18, s20, s33
	s_mov_b32 m0, s18
	s_nop 0
	global_load_lds_dwordx4 v132, s[14:15]
	s_add_i32 m0, s18, 0x2000
	s_nop 0
	global_load_lds_dwordx4 v136, s[14:15]
	s_waitcnt vmcnt(6)
	s_barrier
	v_mfma_f32_16x16x32_bf16 v[54:57], v[210:213], v[158:161], v[54:57]
	v_mfma_f32_16x16x32_bf16 v[50:53], v[218:221], v[158:161], v[50:53]
	v_mfma_f32_16x16x32_bf16 v[38:41], v[210:213], v[172:175], v[38:41]
	v_mfma_f32_16x16x32_bf16 v[34:37], v[218:221], v[172:175], v[34:37]
	v_mfma_f32_16x16x32_bf16 v[22:25], v[210:213], v[194:197], v[22:25]
	v_mfma_f32_16x16x32_bf16 v[18:21], v[218:221], v[194:197], v[18:21]
	v_mfma_f32_16x16x32_bf16 v[6:9], v[210:213], v[202:205], v[6:9]
	v_mfma_f32_16x16x32_bf16 v[2:5], v[218:221], v[202:205], v[2:5]
	v_mfma_f32_16x16x32_bf16 v[54:57], v[214:217], v[168:171], v[54:57]
	v_mfma_f32_16x16x32_bf16 v[50:53], v[222:225], v[168:171], v[50:53]
	v_mfma_f32_16x16x32_bf16 v[38:41], v[214:217], v[190:193], v[38:41]
	v_mfma_f32_16x16x32_bf16 v[34:37], v[222:225], v[190:193], v[34:37]
	v_mfma_f32_16x16x32_bf16 v[22:25], v[214:217], v[198:201], v[22:25]
	v_mfma_f32_16x16x32_bf16 v[18:21], v[222:225], v[198:201], v[18:21]
	v_mfma_f32_16x16x32_bf16 v[6:9], v[214:217], v[206:209], v[6:9]
	v_mfma_f32_16x16x32_bf16 v[2:5], v[222:225], v[206:209], v[2:5]
	s_barrier
	s_add_i32 s48, s48, 2
	s_add_u32 s46, s46, 0x100
	s_addc_u32 s47, s47, 0
	s_cmp_gt_u32 s48, 41
	s_mov_b64 s[14:15], s[16:17]
	s_cbranch_scc0 .LBB0_400
	s_ashr_i32 s14, s44, 5
	v_lshl_or_b32 v176, s45, 8, v165
	s_mul_hi_i32 s15, s14, 0x9000
	s_mul_i32 s14, s14, 0x9000
	s_add_u32 s14, s26, s14
	v_ashrrev_i32_e32 v177, 31, v176
	s_addc_u32 s15, s27, s15
	v_lshlrev_b64 v[158:159], 2, v[176:177]
	v_lshl_add_u64 v[160:161], s[14:15], 0, v[158:159]
	global_load_dwordx4 v[142:145], v[160:161], off offset:16
	global_load_dwordx4 v[146:149], v[160:161], off
	v_lshl_add_u32 v162, s44, 8, v1
	v_ashrrev_i32_e32 v163, 31, v162
	v_lshl_add_u32 v131, v162, 12, v158
	global_load_dwordx4 v[188:191], v131, s[2:3] offset:16
	global_load_dwordx4 v[192:195], v131, s[2:3]
	global_load_dwordx4 v[196:199], v131, s[2:3] offset:528
	global_load_dwordx4 v[200:203], v131, s[2:3] offset:512
	v_add_u32_e32 v131, 0x10000, v131
	global_load_dwordx4 v[204:207], v131, s[2:3] offset:16
	global_load_dwordx4 v[208:211], v131, s[2:3]
	global_load_dwordx4 v[212:215], v131, s[2:3] offset:528
	global_load_dwordx4 v[216:219], v131, s[2:3] offset:512
	v_add_u32_e32 v131, 0x10000, v131
	global_load_dwordx4 v[220:223], v131, s[2:3] offset:16
	global_load_dwordx4 v[224:227], v131, s[2:3]
	global_load_dwordx4 v[228:231], v131, s[2:3] offset:528
	global_load_dwordx4 v[236:239], v131, s[2:3] offset:512
	v_add_u32_e32 v131, 0x10000, v131
	global_load_dwordx4 v[246:249], v131, s[2:3] offset:16
	global_load_dwordx4 v[250:253], v131, s[2:3]
	v_mov_b32_e32 v133, v131
	s_mov_b64 s[14:15], 0x80000
	s_and_b64 vcc, exec, s[4:5]
	s_mov_b32 s45, s42
	s_mov_b32 s44, s43
	s_mov_b64 s[16:17], s[8:9]
	s_waitcnt vmcnt(14)
	v_pk_add_f32 v[144:145], v[144:145], 1.0 op_sel_hi:[1,0]
	v_pk_add_f32 v[148:149], v[148:149], 1.0 op_sel_hi:[1,0]
	v_pk_add_f32 v[146:147], v[146:147], 1.0 op_sel_hi:[1,0]
	v_pk_add_f32 v[142:143], v[142:143], 1.0 op_sel_hi:[1,0]
	v_pk_mul_f32 v[150:151], v[148:149], 0.5 op_sel_hi:[1,0]
	v_pk_mul_f32 v[152:153], v[146:147], 0.5 op_sel_hi:[1,0]
	v_pk_mul_f32 v[154:155], v[144:145], 0.5 op_sel_hi:[1,0]
	v_pk_mul_f32 v[156:157], v[142:143], 0.5 op_sel_hi:[1,0]
	global_load_dwordx4 v[146:149], v[160:161], off offset:528
	global_load_dwordx4 v[142:145], v[160:161], off offset:512
	s_waitcnt vmcnt(0)
	v_pk_add_f32 v[148:149], v[148:149], 1.0 op_sel_hi:[1,0]
	v_pk_add_f32 v[144:145], v[144:145], 1.0 op_sel_hi:[1,0]
	v_pk_add_f32 v[160:161], v[142:143], 1.0 op_sel_hi:[1,0]
	v_pk_mul_f32 v[142:143], v[144:145], 0.5 op_sel_hi:[1,0]
	v_pk_mul_f32 v[144:145], v[160:161], 0.5 op_sel_hi:[1,0]
	v_pk_add_f32 v[160:161], v[146:147], 1.0 op_sel_hi:[1,0]
	v_pk_mul_f32 v[146:147], v[148:149], 0.5 op_sel_hi:[1,0]
	v_pk_mul_f32 v[148:149], v[160:161], 0.5 op_sel_hi:[1,0]
	v_lshlrev_b64 v[160:161], 12, v[162:163]
	v_lshl_add_u64 v[168:169], s[2:3], 0, v[160:161]
	v_lshl_add_u64 v[186:187], v[168:169], 0, v[158:159]
	v_mov_b32_e32 v168, v188
	v_mov_b32_e32 v169, v189
	v_mov_b32_e32 v170, v190
	v_mov_b32_e32 v171, v191
	v_mov_b32_e32 v172, v192
	v_mov_b32_e32 v173, v193
	v_mov_b32_e32 v174, v194
	v_mov_b32_e32 v175, v195
	global_load_dwordx4 v[188:191], v133, s[2:3] offset:528
	global_load_dwordx4 v[192:195], v133, s[2:3] offset:512
	v_pk_fma_f32 v[122:123], v[122:123], v[156:157], v[168:169]
	v_pk_fma_f32 v[128:129], v[128:129], v[150:151], v[174:175]
	v_pk_fma_f32 v[126:127], v[126:127], v[152:153], v[172:173]
	v_pk_fma_f32 v[170:171], v[124:125], v[154:155], v[170:171]
	v_cvt_pk_bf16_f32 v124, v126, v127
	v_cvt_pk_bf16_f32 v125, v128, v129
	v_cvt_pk_bf16_f32 v126, v122, v123
	v_lshl_add_u64 v[128:129], s[12:13], 0, v[160:161]
	v_lshlrev_b64 v[122:123], 1, v[176:177]
	v_cvt_pk_bf16_f32 v127, v170, v171
	v_lshl_add_u64 v[128:129], v[128:129], 0, v[122:123]
	global_store_dwordx4 v[128:129], v[124:127], off offset:2048
	s_nop 1
	v_mov_b32_e32 v124, v196
	v_mov_b32_e32 v125, v197
	v_mov_b32_e32 v126, v198
	v_mov_b32_e32 v127, v199
	s_nop 0
	v_mov_b32_e32 v168, v200
	v_mov_b32_e32 v169, v201
	v_mov_b32_e32 v170, v202
	v_mov_b32_e32 v171, v203
	v_add_u32_e32 v133, 0x50000, v133
	global_load_dwordx4 v[196:199], v133, s[2:3] offset:16
	global_load_dwordx4 v[200:203], v133, s[2:3]
	v_pk_fma_f32 v[126:127], v[116:117], v[146:147], v[126:127]
	v_pk_fma_f32 v[120:121], v[120:121], v[142:143], v[170:171]
	v_pk_fma_f32 v[118:119], v[118:119], v[144:145], v[168:169]
	v_pk_fma_f32 v[116:117], v[114:115], v[148:149], v[124:125]
	v_cvt_pk_bf16_f32 v114, v118, v119
	v_cvt_pk_bf16_f32 v115, v120, v121
	v_cvt_pk_bf16_f32 v116, v116, v117
	v_cvt_pk_bf16_f32 v117, v126, v127
	global_store_dwordx4 v[128:129], v[114:117], off offset:2304
	s_nop 1
	v_or_b32_e32 v114, 16, v162
	v_ashrrev_i32_e32 v115, 31, v114
	v_lshlrev_b64 v[124:125], 12, v[114:115]
	v_lshl_add_u64 v[114:115], s[2:3], 0, v[124:125]
	v_lshl_add_u64 v[126:127], v[114:115], 0, v[158:159]
	v_mov_b32_e32 v114, v204
	v_mov_b32_e32 v115, v205
	v_mov_b32_e32 v116, v206
	v_mov_b32_e32 v117, v207
	v_mov_b32_e32 v118, v208
	v_mov_b32_e32 v119, v209
	v_mov_b32_e32 v120, v210
	v_mov_b32_e32 v121, v211
	global_load_dwordx4 v[204:207], v133, s[2:3] offset:528
	global_load_dwordx4 v[208:211], v133, s[2:3] offset:512
	v_pk_fma_f32 v[116:117], v[108:109], v[154:155], v[116:117]
	v_pk_fma_f32 v[110:111], v[110:111], v[152:153], v[118:119]
	v_pk_fma_f32 v[112:113], v[112:113], v[150:151], v[120:121]
	v_pk_fma_f32 v[108:109], v[106:107], v[156:157], v[114:115]
	v_cvt_pk_bf16_f32 v106, v110, v111
	v_lshl_add_u64 v[110:111], s[12:13], 0, v[124:125]
	v_cvt_pk_bf16_f32 v107, v112, v113
	v_cvt_pk_bf16_f32 v108, v108, v109
	v_cvt_pk_bf16_f32 v109, v116, v117
	v_lshl_add_u64 v[114:115], v[110:111], 0, v[122:123]
	global_store_dwordx4 v[114:115], v[106:109], off offset:2048
	s_nop 1
	v_mov_b32_e32 v106, v212
	v_mov_b32_e32 v107, v213
	v_mov_b32_e32 v108, v214
	v_mov_b32_e32 v109, v215
	s_nop 0
	v_mov_b32_e32 v110, v216
	v_mov_b32_e32 v111, v217
	v_mov_b32_e32 v112, v218
	v_mov_b32_e32 v113, v219
	v_add_u32_e32 v133, 0x10000, v133
	global_load_dwordx4 v[212:215], v133, s[2:3] offset:16
	global_load_dwordx4 v[216:219], v133, s[2:3]
	v_pk_fma_f32 v[108:109], v[100:101], v[146:147], v[108:109]
	v_pk_fma_f32 v[104:105], v[104:105], v[142:143], v[112:113]
	v_pk_fma_f32 v[102:103], v[102:103], v[144:145], v[110:111]
	v_pk_fma_f32 v[100:101], v[98:99], v[148:149], v[106:107]
	v_cvt_pk_bf16_f32 v98, v102, v103
	v_cvt_pk_bf16_f32 v99, v104, v105
	v_cvt_pk_bf16_f32 v100, v100, v101
	v_cvt_pk_bf16_f32 v101, v108, v109
	global_store_dwordx4 v[114:115], v[98:101], off offset:2304
	s_nop 1
	v_or_b32_e32 v98, 32, v162
	v_ashrrev_i32_e32 v99, 31, v98
	v_lshlrev_b64 v[106:107], 12, v[98:99]
	v_lshl_add_u64 v[98:99], s[2:3], 0, v[106:107]
	v_lshl_add_u64 v[108:109], v[98:99], 0, v[158:159]
	v_mov_b32_e32 v98, v220
	v_mov_b32_e32 v99, v221
	v_mov_b32_e32 v100, v222
	v_mov_b32_e32 v101, v223
	v_mov_b32_e32 v102, v224
	v_mov_b32_e32 v103, v225
	v_mov_b32_e32 v104, v226
	v_mov_b32_e32 v105, v227
	global_load_dwordx4 v[220:223], v133, s[2:3] offset:528
	global_load_dwordx4 v[224:227], v133, s[2:3] offset:512
	v_pk_fma_f32 v[100:101], v[92:93], v[154:155], v[100:101]
	v_pk_fma_f32 v[94:95], v[94:95], v[152:153], v[102:103]
	v_pk_fma_f32 v[96:97], v[96:97], v[150:151], v[104:105]
	v_pk_fma_f32 v[92:93], v[90:91], v[156:157], v[98:99]
	v_cvt_pk_bf16_f32 v90, v94, v95
	v_lshl_add_u64 v[94:95], s[12:13], 0, v[106:107]
	v_cvt_pk_bf16_f32 v91, v96, v97
	v_cvt_pk_bf16_f32 v92, v92, v93
	v_cvt_pk_bf16_f32 v93, v100, v101
	v_lshl_add_u64 v[98:99], v[94:95], 0, v[122:123]
	global_store_dwordx4 v[98:99], v[90:93], off offset:2048
	s_nop 1
	v_mov_b32_e32 v90, v228
	v_mov_b32_e32 v91, v229
	v_mov_b32_e32 v92, v230
	v_mov_b32_e32 v93, v231
	s_nop 0
	v_mov_b32_e32 v94, v236
	v_mov_b32_e32 v95, v237
	v_mov_b32_e32 v96, v238
	v_mov_b32_e32 v97, v239
	v_add_u32_e32 v133, 0x10000, v133
	global_load_dwordx4 v[228:231], v133, s[2:3] offset:16
	global_load_dwordx4 v[236:239], v133, s[2:3]
	v_pk_fma_f32 v[92:93], v[84:85], v[146:147], v[92:93]
	v_pk_fma_f32 v[88:89], v[88:89], v[142:143], v[96:97]
	v_pk_fma_f32 v[86:87], v[86:87], v[144:145], v[94:95]
	v_pk_fma_f32 v[84:85], v[82:83], v[148:149], v[90:91]
	v_cvt_pk_bf16_f32 v82, v86, v87
	v_cvt_pk_bf16_f32 v83, v88, v89
	v_cvt_pk_bf16_f32 v84, v84, v85
	v_cvt_pk_bf16_f32 v85, v92, v93
	global_store_dwordx4 v[98:99], v[82:85], off offset:2304
	s_nop 1
	v_or_b32_e32 v82, 48, v162
	v_ashrrev_i32_e32 v83, 31, v82
	v_lshlrev_b64 v[90:91], 12, v[82:83]
	v_lshl_add_u64 v[82:83], s[2:3], 0, v[90:91]
	v_lshl_add_u64 v[92:93], v[82:83], 0, v[158:159]
	v_mov_b32_e32 v82, v246
	v_mov_b32_e32 v83, v247
	v_mov_b32_e32 v84, v248
	v_mov_b32_e32 v85, v249
	v_mov_b32_e32 v86, v250
	v_mov_b32_e32 v87, v251
	v_mov_b32_e32 v88, v252
	v_mov_b32_e32 v89, v253
	global_load_dwordx4 v[246:249], v133, s[2:3] offset:528
	global_load_dwordx4 v[250:253], v133, s[2:3] offset:512
	v_pk_fma_f32 v[84:85], v[76:77], v[154:155], v[84:85]
	v_pk_fma_f32 v[78:79], v[78:79], v[152:153], v[86:87]
	v_pk_fma_f32 v[80:81], v[80:81], v[150:151], v[88:89]
	v_pk_fma_f32 v[76:77], v[74:75], v[156:157], v[82:83]
	v_cvt_pk_bf16_f32 v74, v78, v79
	v_lshl_add_u64 v[78:79], s[12:13], 0, v[90:91]
	v_cvt_pk_bf16_f32 v75, v80, v81
	v_cvt_pk_bf16_f32 v76, v76, v77
	v_cvt_pk_bf16_f32 v77, v84, v85
	v_lshl_add_u64 v[82:83], v[78:79], 0, v[122:123]
	global_store_dwordx4 v[82:83], v[74:77], off offset:2048
	s_nop 1
	s_waitcnt vmcnt(19)
	v_mov_b32_e32 v74, v188
	v_mov_b32_e32 v75, v189
	v_mov_b32_e32 v76, v190
	v_mov_b32_e32 v77, v191
	s_nop 0
	v_mov_b32_e32 v78, v192
	v_mov_b32_e32 v79, v193
	v_mov_b32_e32 v80, v194
	v_mov_b32_e32 v81, v195
	v_add_u32_e32 v133, 0x10000, v133
	global_load_dwordx4 v[188:191], v133, s[2:3] offset:16
	global_load_dwordx4 v[192:195], v133, s[2:3]
	v_pk_fma_f32 v[76:77], v[68:69], v[146:147], v[76:77]
	v_pk_fma_f32 v[72:73], v[72:73], v[142:143], v[80:81]
	v_pk_fma_f32 v[70:71], v[70:71], v[144:145], v[78:79]
	v_pk_fma_f32 v[68:69], v[66:67], v[148:149], v[74:75]
	v_cvt_pk_bf16_f32 v66, v70, v71
	v_cvt_pk_bf16_f32 v67, v72, v73
	v_cvt_pk_bf16_f32 v68, v68, v69
	v_cvt_pk_bf16_f32 v69, v76, v77
	v_lshl_add_u64 v[74:75], v[160:161], 0, s[14:15]
	global_store_dwordx4 v[82:83], v[66:69], off offset:2304
	s_mov_b64 s[14:15], 0x90000
	s_nop 0
	v_lshl_add_u64 v[66:67], s[2:3], 0, v[74:75]
	v_lshl_add_u64 v[76:77], v[66:67], 0, v[158:159]
	s_waitcnt vmcnt(19)
	v_mov_b32_e32 v66, v196
	v_mov_b32_e32 v67, v197
	v_mov_b32_e32 v68, v198
	v_mov_b32_e32 v69, v199
	v_mov_b32_e32 v70, v200
	v_mov_b32_e32 v71, v201
	v_mov_b32_e32 v72, v202
	v_mov_b32_e32 v73, v203
	global_load_dwordx4 v[196:199], v133, s[2:3] offset:528
	global_load_dwordx4 v[200:203], v133, s[2:3] offset:512
	v_pk_fma_f32 v[68:69], v[60:61], v[154:155], v[68:69]
	v_pk_fma_f32 v[62:63], v[62:63], v[152:153], v[70:71]
	v_pk_fma_f32 v[64:65], v[64:65], v[150:151], v[72:73]
	v_pk_fma_f32 v[60:61], v[58:59], v[156:157], v[66:67]
	v_cvt_pk_bf16_f32 v58, v62, v63
	v_lshl_add_u64 v[62:63], s[12:13], 0, v[74:75]
	v_cvt_pk_bf16_f32 v59, v64, v65
	v_cvt_pk_bf16_f32 v60, v60, v61
	v_cvt_pk_bf16_f32 v61, v68, v69
	v_lshl_add_u64 v[66:67], v[62:63], 0, v[122:123]
	global_store_dwordx4 v[66:67], v[58:61], off offset:2048
	s_nop 1
	s_waitcnt vmcnt(19)
	v_mov_b32_e32 v58, v204
	v_mov_b32_e32 v59, v205
	v_mov_b32_e32 v60, v206
	v_mov_b32_e32 v61, v207
	s_nop 0
	v_mov_b32_e32 v62, v208
	v_mov_b32_e32 v63, v209
	v_mov_b32_e32 v64, v210
	v_mov_b32_e32 v65, v211
	s_nop 0
	v_pk_fma_f32 v[60:61], v[52:53], v[146:147], v[60:61]
	v_pk_fma_f32 v[56:57], v[56:57], v[142:143], v[64:65]
	v_pk_fma_f32 v[54:55], v[54:55], v[144:145], v[62:63]
	v_pk_fma_f32 v[52:53], v[50:51], v[148:149], v[58:59]
	v_cvt_pk_bf16_f32 v50, v54, v55
	v_cvt_pk_bf16_f32 v51, v56, v57
	v_cvt_pk_bf16_f32 v52, v52, v53
	v_cvt_pk_bf16_f32 v53, v60, v61
	v_lshl_add_u64 v[58:59], v[160:161], 0, s[14:15]
	global_store_dwordx4 v[66:67], v[50:53], off offset:2304
	s_mov_b64 s[14:15], 0xa0000
	s_nop 0
	v_lshl_add_u64 v[50:51], s[2:3], 0, v[58:59]
	v_lshl_add_u64 v[60:61], v[50:51], 0, v[158:159]
	s_waitcnt vmcnt(17)
	v_mov_b32_e32 v50, v212
	v_mov_b32_e32 v51, v213
	v_mov_b32_e32 v52, v214
	v_mov_b32_e32 v53, v215
	v_mov_b32_e32 v54, v216
	v_mov_b32_e32 v55, v217
	v_mov_b32_e32 v56, v218
	v_mov_b32_e32 v57, v219
	s_nop 0
	v_pk_fma_f32 v[52:53], v[44:45], v[154:155], v[52:53]
	v_pk_fma_f32 v[46:47], v[46:47], v[152:153], v[54:55]
	v_pk_fma_f32 v[48:49], v[48:49], v[150:151], v[56:57]
	v_pk_fma_f32 v[44:45], v[42:43], v[156:157], v[50:51]
	v_cvt_pk_bf16_f32 v42, v46, v47
	v_lshl_add_u64 v[46:47], s[12:13], 0, v[58:59]
	v_cvt_pk_bf16_f32 v43, v48, v49
	v_cvt_pk_bf16_f32 v44, v44, v45
	v_cvt_pk_bf16_f32 v45, v52, v53
	v_lshl_add_u64 v[50:51], v[46:47], 0, v[122:123]
	global_store_dwordx4 v[50:51], v[42:45], off offset:2048
	s_nop 1
	s_waitcnt vmcnt(15)
	v_mov_b32_e32 v42, v220
	v_mov_b32_e32 v43, v221
	v_mov_b32_e32 v44, v222
	v_mov_b32_e32 v45, v223
	s_nop 0
	v_mov_b32_e32 v46, v224
	v_mov_b32_e32 v47, v225
	v_mov_b32_e32 v48, v226
	v_mov_b32_e32 v49, v227
	s_nop 0
	v_pk_fma_f32 v[44:45], v[36:37], v[146:147], v[44:45]
	v_pk_fma_f32 v[40:41], v[40:41], v[142:143], v[48:49]
	v_pk_fma_f32 v[38:39], v[38:39], v[144:145], v[46:47]
	v_pk_fma_f32 v[36:37], v[34:35], v[148:149], v[42:43]
	v_cvt_pk_bf16_f32 v34, v38, v39
	v_cvt_pk_bf16_f32 v35, v40, v41
	v_cvt_pk_bf16_f32 v36, v36, v37
	v_cvt_pk_bf16_f32 v37, v44, v45
	v_lshl_add_u64 v[42:43], v[160:161], 0, s[14:15]
	global_store_dwordx4 v[50:51], v[34:37], off offset:2304
	s_mov_b64 s[14:15], 0xb0000
	s_nop 0
	v_lshl_add_u64 v[34:35], s[2:3], 0, v[42:43]
	v_lshl_add_u64 v[44:45], v[34:35], 0, v[158:159]
	s_waitcnt vmcnt(13)
	v_mov_b32_e32 v34, v228
	v_mov_b32_e32 v35, v229
	v_mov_b32_e32 v36, v230
	v_mov_b32_e32 v37, v231
	v_mov_b32_e32 v38, v236
	v_mov_b32_e32 v39, v237
	v_mov_b32_e32 v40, v238
	v_mov_b32_e32 v41, v239
	s_nop 0
	v_pk_fma_f32 v[36:37], v[28:29], v[154:155], v[36:37]
	v_pk_fma_f32 v[30:31], v[30:31], v[152:153], v[38:39]
	v_pk_fma_f32 v[32:33], v[32:33], v[150:151], v[40:41]
	v_pk_fma_f32 v[28:29], v[26:27], v[156:157], v[34:35]
	v_cvt_pk_bf16_f32 v26, v30, v31
	v_lshl_add_u64 v[30:31], s[12:13], 0, v[42:43]
	v_cvt_pk_bf16_f32 v27, v32, v33
	v_cvt_pk_bf16_f32 v28, v28, v29
	v_cvt_pk_bf16_f32 v29, v36, v37
	v_lshl_add_u64 v[34:35], v[30:31], 0, v[122:123]
	global_store_dwordx4 v[34:35], v[26:29], off offset:2048
	s_nop 1
	s_waitcnt vmcnt(11)
	v_mov_b32_e32 v26, v246
	v_mov_b32_e32 v27, v247
	v_mov_b32_e32 v28, v248
	v_mov_b32_e32 v29, v249
	s_nop 0
	v_mov_b32_e32 v30, v250
	v_mov_b32_e32 v31, v251
	v_mov_b32_e32 v32, v252
	v_mov_b32_e32 v33, v253
	s_nop 0
	v_pk_fma_f32 v[28:29], v[20:21], v[146:147], v[28:29]
	v_pk_fma_f32 v[24:25], v[24:25], v[142:143], v[32:33]
	v_pk_fma_f32 v[22:23], v[22:23], v[144:145], v[30:31]
	v_pk_fma_f32 v[20:21], v[18:19], v[148:149], v[26:27]
	v_cvt_pk_bf16_f32 v18, v22, v23
	v_cvt_pk_bf16_f32 v19, v24, v25
	v_cvt_pk_bf16_f32 v20, v20, v21
	v_cvt_pk_bf16_f32 v21, v28, v29
	v_lshl_add_u64 v[26:27], v[160:161], 0, s[14:15]
	global_store_dwordx4 v[34:35], v[18:21], off offset:2304
	s_mov_b64 s[14:15], s[6:7]
	s_nop 0
	v_lshl_add_u64 v[18:19], s[2:3], 0, v[26:27]
	v_lshl_add_u64 v[28:29], v[18:19], 0, v[158:159]
	s_waitcnt vmcnt(9)
	v_mov_b32_e32 v18, v188
	v_mov_b32_e32 v19, v189
	v_mov_b32_e32 v20, v190
	v_mov_b32_e32 v21, v191
	v_mov_b32_e32 v22, v192
	v_mov_b32_e32 v23, v193
	v_mov_b32_e32 v24, v194
	v_mov_b32_e32 v25, v195
	s_nop 0
	v_pk_fma_f32 v[20:21], v[12:13], v[154:155], v[20:21]
	v_pk_fma_f32 v[14:15], v[14:15], v[152:153], v[22:23]
	v_pk_fma_f32 v[16:17], v[16:17], v[150:151], v[24:25]
	v_pk_fma_f32 v[12:13], v[10:11], v[156:157], v[18:19]
	v_cvt_pk_bf16_f32 v10, v14, v15
	v_lshl_add_u64 v[14:15], s[12:13], 0, v[26:27]
	v_cvt_pk_bf16_f32 v11, v16, v17
	v_cvt_pk_bf16_f32 v12, v12, v13
	v_cvt_pk_bf16_f32 v13, v20, v21
	v_lshl_add_u64 v[18:19], v[14:15], 0, v[122:123]
	global_store_dwordx4 v[18:19], v[10:13], off offset:2048
	s_nop 1
	s_waitcnt vmcnt(7)
	v_mov_b32_e32 v10, v196
	v_mov_b32_e32 v11, v197
	v_mov_b32_e32 v12, v198
	v_mov_b32_e32 v13, v199
	s_nop 0
	v_mov_b32_e32 v14, v200
	v_mov_b32_e32 v15, v201
	v_mov_b32_e32 v16, v202
	v_mov_b32_e32 v17, v203
	s_nop 0
	v_pk_fma_f32 v[12:13], v[4:5], v[146:147], v[12:13]
	v_pk_fma_f32 v[8:9], v[8:9], v[142:143], v[16:17]
	v_pk_fma_f32 v[6:7], v[6:7], v[144:145], v[14:15]
	v_pk_fma_f32 v[4:5], v[2:3], v[148:149], v[10:11]
	v_cvt_pk_bf16_f32 v2, v6, v7
	v_cvt_pk_bf16_f32 v3, v8, v9
	v_cvt_pk_bf16_f32 v4, v4, v5
	v_cvt_pk_bf16_f32 v5, v12, v13
	global_store_dwordx4 v[18:19], v[2:5], off offset:2304
	s_cbranch_vccz .LBB0_389
	s_waitcnt vmcnt(0)
	s_cmpk_gt_u32 s30, 0xff
	s_cbranch_scc1 .LBB0_404
	s_barrier

.LBB0_1408:
	s_add_u32 s16, s14, s6
	s_addc_u32 s17, s15, s7
	s_add_u32 s16, s16, 0x100
	s_addc_u32 s17, s17, 0
	s_add_u32 s48, s45, s6
	s_addc_u32 s49, s46, s7
	s_add_i32 s50, 0, 0x10000
	v_add_u32_e32 v158, s50, v164
	ds_read_b128 v[146:149], v158
	ds_read_b128 v[150:153], v158 offset:1024
	ds_read_b128 v[154:157], v158 offset:2048
	ds_read_b128 v[158:161], v158 offset:3072
	s_cmpk_eq_i32 s6, 0xf00
	s_cselect_b32 s19, s11, s17
	s_cselect_b32 s18, s10, s16
	s_cselect_b32 s17, s3, s49
	s_cselect_b32 s16, s44, s48
	v_lshl_add_u64 v[162:163], v[142:143], 0, s[6:7]
	s_add_i32 m0, s30, 0xc000
	ds_read_b128 v[168:171], v166
	ds_read_b128 v[172:175], v166 offset:1024
	ds_read_b128 v[186:189], v166 offset:2048
	ds_read_b128 v[190:193], v166 offset:3072
	ds_read_b128 v[194:197], v166 offset:4096
	ds_read_b128 v[198:201], v166 offset:5120
	ds_read_b128 v[202:205], v166 offset:6144
	ds_read_b128 v[206:209], v166 offset:7168
	global_load_lds_dwordx4 v[162:163], off
	v_lshl_add_u64 v[162:163], v[144:145], 0, s[6:7]
	s_add_i32 m0, s30, 0xe000
	s_nop 0
	global_load_lds_dwordx4 v[162:163], off
	s_waitcnt lgkmcnt(8)
	s_barrier
	s_waitcnt lgkmcnt(0)
	s_waitcnt lgkmcnt(0)
	v_mfma_f32_16x16x32_bf16 v[126:129], v[146:149], v[168:171], v[126:129]
	v_mfma_f32_16x16x32_bf16 v[122:125], v[154:157], v[168:171], v[122:125]
	v_mfma_f32_16x16x32_bf16 v[110:113], v[146:149], v[186:189], v[110:113]
	v_mfma_f32_16x16x32_bf16 v[106:109], v[154:157], v[186:189], v[106:109]
	v_mfma_f32_16x16x32_bf16 v[94:97], v[146:149], v[194:197], v[94:97]
	v_mfma_f32_16x16x32_bf16 v[90:93], v[154:157], v[194:197], v[90:93]
	v_mfma_f32_16x16x32_bf16 v[78:81], v[146:149], v[202:205], v[78:81]
	v_mfma_f32_16x16x32_bf16 v[74:77], v[154:157], v[202:205], v[74:77]
	v_mfma_f32_16x16x32_bf16 v[126:129], v[150:153], v[172:175], v[126:129]
	v_mfma_f32_16x16x32_bf16 v[122:125], v[158:161], v[172:175], v[122:125]
	v_mfma_f32_16x16x32_bf16 v[110:113], v[150:153], v[190:193], v[110:113]
	v_mfma_f32_16x16x32_bf16 v[106:109], v[158:161], v[190:193], v[106:109]
	v_mfma_f32_16x16x32_bf16 v[94:97], v[150:153], v[198:201], v[94:97]
	v_mfma_f32_16x16x32_bf16 v[90:93], v[158:161], v[198:201], v[90:93]
	v_mfma_f32_16x16x32_bf16 v[78:81], v[150:153], v[206:209], v[78:81]
	v_mfma_f32_16x16x32_bf16 v[74:77], v[158:161], v[206:209], v[74:77]
	s_barrier
	s_add_i32 s51, 0, 0x14000
	v_add_u32_e32 v162, s51, v164
	s_add_i32 s48, s50, s29
	ds_read_b128 v[210:213], v162
	ds_read_b128 v[214:217], v162 offset:1024
	ds_read_b128 v[218:221], v162 offset:2048
	ds_read_b128 v[222:225], v162 offset:3072
	s_add_u32 s64, s16, 0x80
	s_addc_u32 s65, s17, 0
	s_mov_b32 m0, s48
	s_nop 0
	global_load_lds_dwordx4 v132, s[16:17]
	s_add_i32 m0, s48, 0x2000
	s_nop 0
	global_load_lds_dwordx4 v136, s[16:17]
	s_barrier
	s_waitcnt lgkmcnt(0)
	s_waitcnt lgkmcnt(0)
	v_mfma_f32_16x16x32_bf16 v[118:121], v[210:213], v[168:171], v[118:121]
	v_mfma_f32_16x16x32_bf16 v[114:117], v[218:221], v[168:171], v[114:117]
	v_mfma_f32_16x16x32_bf16 v[102:105], v[210:213], v[186:189], v[102:105]
	v_mfma_f32_16x16x32_bf16 v[98:101], v[218:221], v[186:189], v[98:101]
	v_mfma_f32_16x16x32_bf16 v[86:89], v[210:213], v[194:197], v[86:89]
	v_mfma_f32_16x16x32_bf16 v[82:85], v[218:221], v[194:197], v[82:85]
	v_mfma_f32_16x16x32_bf16 v[70:73], v[210:213], v[202:205], v[70:73]
	v_mfma_f32_16x16x32_bf16 v[66:69], v[218:221], v[202:205], v[66:69]
	v_mfma_f32_16x16x32_bf16 v[118:121], v[214:217], v[172:175], v[118:121]
	v_mfma_f32_16x16x32_bf16 v[114:117], v[222:225], v[172:175], v[114:117]
	v_mfma_f32_16x16x32_bf16 v[102:105], v[214:217], v[190:193], v[102:105]
	v_mfma_f32_16x16x32_bf16 v[98:101], v[222:225], v[190:193], v[98:101]
	v_mfma_f32_16x16x32_bf16 v[86:89], v[214:217], v[198:201], v[86:89]
	v_mfma_f32_16x16x32_bf16 v[82:85], v[222:225], v[198:201], v[82:85]
	v_mfma_f32_16x16x32_bf16 v[70:73], v[214:217], v[206:209], v[70:73]
	v_mfma_f32_16x16x32_bf16 v[66:69], v[222:225], v[206:209], v[66:69]
	s_barrier
	s_mov_b32 m0, s30
	s_add_u32 s62, s18, 0x80
	s_addc_u32 s63, s19, 0
	ds_read_b128 v[168:171], v166 offset:16384
	ds_read_b128 v[172:175], v166 offset:17408
	ds_read_b128 v[186:189], v166 offset:18432
	ds_read_b128 v[190:193], v166 offset:19456
	ds_read_b128 v[194:197], v166 offset:20480
	ds_read_b128 v[198:201], v166 offset:21504
	ds_read_b128 v[202:205], v166 offset:22528
	ds_read_b128 v[206:209], v166 offset:23552
	global_load_lds_dwordx4 v130, s[18:19]
	s_mov_b32 m0, s31
	s_nop 0
	global_load_lds_dwordx4 v134, s[18:19]
	s_barrier
	s_waitcnt lgkmcnt(0)
	s_waitcnt lgkmcnt(0)
	v_mfma_f32_16x16x32_bf16 v[62:65], v[146:149], v[168:171], v[62:65]
	v_mfma_f32_16x16x32_bf16 v[58:61], v[154:157], v[168:171], v[58:61]
	v_mfma_f32_16x16x32_bf16 v[46:49], v[146:149], v[186:189], v[46:49]
	v_mfma_f32_16x16x32_bf16 v[42:45], v[154:157], v[186:189], v[42:45]
	v_mfma_f32_16x16x32_bf16 v[30:33], v[146:149], v[194:197], v[30:33]
	v_mfma_f32_16x16x32_bf16 v[26:29], v[154:157], v[194:197], v[26:29]
	v_mfma_f32_16x16x32_bf16 v[14:17], v[146:149], v[202:205], v[14:17]
	v_mfma_f32_16x16x32_bf16 v[10:13], v[154:157], v[202:205], v[10:13]
	v_mfma_f32_16x16x32_bf16 v[62:65], v[150:153], v[172:175], v[62:65]
	v_mfma_f32_16x16x32_bf16 v[58:61], v[158:161], v[172:175], v[58:61]
	v_mfma_f32_16x16x32_bf16 v[46:49], v[150:153], v[190:193], v[46:49]
	v_mfma_f32_16x16x32_bf16 v[42:45], v[158:161], v[190:193], v[42:45]
	v_mfma_f32_16x16x32_bf16 v[30:33], v[150:153], v[198:201], v[30:33]
	v_mfma_f32_16x16x32_bf16 v[26:29], v[158:161], v[198:201], v[26:29]
	v_mfma_f32_16x16x32_bf16 v[14:17], v[150:153], v[206:209], v[14:17]
	v_mfma_f32_16x16x32_bf16 v[10:13], v[158:161], v[206:209], v[10:13]
	s_barrier
	s_add_u32 s48, s16, 0x80000
	s_addc_u32 s49, s17, 0
	s_add_i32 s50, s51, s29
	s_mov_b32 m0, s50
	s_nop 0
	global_load_lds_dwordx4 v132, s[48:49]
	s_add_i32 m0, s50, 0x2000
	s_nop 0
	global_load_lds_dwordx4 v136, s[48:49]
	s_waitcnt vmcnt(6)
	s_barrier
	v_mfma_f32_16x16x32_bf16 v[54:57], v[210:213], v[168:171], v[54:57]
	v_mfma_f32_16x16x32_bf16 v[50:53], v[218:221], v[168:171], v[50:53]
	v_mfma_f32_16x16x32_bf16 v[38:41], v[210:213], v[186:189], v[38:41]
	v_mfma_f32_16x16x32_bf16 v[34:37], v[218:221], v[186:189], v[34:37]
	v_mfma_f32_16x16x32_bf16 v[22:25], v[210:213], v[194:197], v[22:25]
	v_mfma_f32_16x16x32_bf16 v[18:21], v[218:221], v[194:197], v[18:21]
	v_mfma_f32_16x16x32_bf16 v[6:9], v[210:213], v[202:205], v[6:9]
	v_mfma_f32_16x16x32_bf16 v[2:5], v[218:221], v[202:205], v[2:5]
	v_mfma_f32_16x16x32_bf16 v[54:57], v[214:217], v[172:175], v[54:57]
	v_mfma_f32_16x16x32_bf16 v[50:53], v[222:225], v[172:175], v[50:53]
	v_mfma_f32_16x16x32_bf16 v[38:41], v[214:217], v[190:193], v[38:41]
	v_mfma_f32_16x16x32_bf16 v[34:37], v[222:225], v[190:193], v[34:37]
	v_mfma_f32_16x16x32_bf16 v[22:25], v[214:217], v[198:201], v[22:25]
	v_mfma_f32_16x16x32_bf16 v[18:21], v[222:225], v[198:201], v[18:21]
	v_mfma_f32_16x16x32_bf16 v[6:9], v[214:217], v[206:209], v[6:9]
	v_mfma_f32_16x16x32_bf16 v[2:5], v[222:225], v[206:209], v[2:5]
	s_barrier
	s_add_i32 s48, 0, 0x18000
	v_add_u32_e32 v158, s48, v164
	ds_read_b128 v[146:149], v158
	ds_read_b128 v[150:153], v158 offset:1024
	ds_read_b128 v[154:157], v158 offset:2048
	ds_read_b128 v[158:161], v158 offset:3072
	s_add_u32 s18, s18, s80
	s_addc_u32 s19, s19, 0
	s_mov_b32 m0, s34
	ds_read_b128 v[168:171], v166 offset:32768
	ds_read_b128 v[172:175], v166 offset:33792
	ds_read_b128 v[186:189], v166 offset:34816
	ds_read_b128 v[190:193], v166 offset:35840
	ds_read_b128 v[194:197], v166 offset:36864
	ds_read_b128 v[198:201], v166 offset:37888
	ds_read_b128 v[202:205], v166 offset:38912
	ds_read_b128 v[206:209], v166 offset:39936
	global_load_lds_dwordx4 v130, s[18:19]
	s_mov_b32 m0, s35
	s_nop 0
	global_load_lds_dwordx4 v134, s[18:19]
	s_waitcnt lgkmcnt(8)
	s_barrier
	s_waitcnt lgkmcnt(0)
	s_waitcnt lgkmcnt(0)
	v_mfma_f32_16x16x32_bf16 v[126:129], v[146:149], v[168:171], v[126:129]
	v_mfma_f32_16x16x32_bf16 v[122:125], v[154:157], v[168:171], v[122:125]
	v_mfma_f32_16x16x32_bf16 v[110:113], v[146:149], v[186:189], v[110:113]
	v_mfma_f32_16x16x32_bf16 v[106:109], v[154:157], v[186:189], v[106:109]
	v_mfma_f32_16x16x32_bf16 v[94:97], v[146:149], v[194:197], v[94:97]
	v_mfma_f32_16x16x32_bf16 v[90:93], v[154:157], v[194:197], v[90:93]
	v_mfma_f32_16x16x32_bf16 v[78:81], v[146:149], v[202:205], v[78:81]
	v_mfma_f32_16x16x32_bf16 v[74:77], v[154:157], v[202:205], v[74:77]
	v_mfma_f32_16x16x32_bf16 v[126:129], v[150:153], v[172:175], v[126:129]
	v_mfma_f32_16x16x32_bf16 v[122:125], v[158:161], v[172:175], v[122:125]
	v_mfma_f32_16x16x32_bf16 v[110:113], v[150:153], v[190:193], v[110:113]
	v_mfma_f32_16x16x32_bf16 v[106:109], v[158:161], v[190:193], v[106:109]
	v_mfma_f32_16x16x32_bf16 v[94:97], v[150:153], v[198:201], v[94:97]
	v_mfma_f32_16x16x32_bf16 v[90:93], v[158:161], v[198:201], v[90:93]
	v_mfma_f32_16x16x32_bf16 v[78:81], v[150:153], v[206:209], v[78:81]
	v_mfma_f32_16x16x32_bf16 v[74:77], v[158:161], v[206:209], v[74:77]
	s_barrier
	s_add_i32 s18, 0, 0x1c000
	s_add_i32 s19, s48, s29
	v_add_u32_e32 v167, s18, v164
	s_mov_b32 m0, s19
	ds_read_b128 v[210:213], v167
	ds_read_b128 v[214:217], v167 offset:1024
	ds_read_b128 v[218:221], v167 offset:2048
	ds_read_b128 v[222:225], v167 offset:3072
	global_load_lds_dwordx4 v132, s[64:65]
	s_add_i32 m0, s19, 0x2000
	s_nop 0
	global_load_lds_dwordx4 v136, s[64:65]
	s_barrier
	s_waitcnt lgkmcnt(0)
	s_waitcnt lgkmcnt(0)
	v_mfma_f32_16x16x32_bf16 v[118:121], v[210:213], v[168:171], v[118:121]
	v_mfma_f32_16x16x32_bf16 v[114:117], v[218:221], v[168:171], v[114:117]
	v_mfma_f32_16x16x32_bf16 v[102:105], v[210:213], v[186:189], v[102:105]
	v_mfma_f32_16x16x32_bf16 v[98:101], v[218:221], v[186:189], v[98:101]
	v_mfma_f32_16x16x32_bf16 v[86:89], v[210:213], v[194:197], v[86:89]
	v_mfma_f32_16x16x32_bf16 v[82:85], v[218:221], v[194:197], v[82:85]
	v_mfma_f32_16x16x32_bf16 v[70:73], v[210:213], v[202:205], v[70:73]
	v_mfma_f32_16x16x32_bf16 v[66:69], v[218:221], v[202:205], v[66:69]
	v_mfma_f32_16x16x32_bf16 v[118:121], v[214:217], v[172:175], v[118:121]
	v_mfma_f32_16x16x32_bf16 v[114:117], v[222:225], v[172:175], v[114:117]
	v_mfma_f32_16x16x32_bf16 v[102:105], v[214:217], v[190:193], v[102:105]
	v_mfma_f32_16x16x32_bf16 v[98:101], v[222:225], v[190:193], v[98:101]
	v_mfma_f32_16x16x32_bf16 v[86:89], v[214:217], v[198:201], v[86:89]
	v_mfma_f32_16x16x32_bf16 v[82:85], v[222:225], v[198:201], v[82:85]
	v_mfma_f32_16x16x32_bf16 v[70:73], v[214:217], v[206:209], v[70:73]
	v_mfma_f32_16x16x32_bf16 v[66:69], v[222:225], v[206:209], v[66:69]
	s_barrier
	s_mov_b32 m0, s38
	ds_read_b128 v[168:171], v166 offset:49152
	ds_read_b128 v[172:175], v166 offset:50176
	ds_read_b128 v[186:189], v166 offset:51200
	ds_read_b128 v[190:193], v166 offset:52224
	ds_read_b128 v[194:197], v166 offset:53248
	ds_read_b128 v[198:201], v166 offset:54272
	ds_read_b128 v[202:205], v166 offset:55296
	ds_read_b128 v[206:209], v166 offset:56320
	global_load_lds_dwordx4 v130, s[62:63]
	s_mov_b32 m0, s39
	s_nop 0
	global_load_lds_dwordx4 v134, s[62:63]
	s_barrier
	s_waitcnt lgkmcnt(0)
	s_waitcnt lgkmcnt(0)
	v_mfma_f32_16x16x32_bf16 v[62:65], v[146:149], v[168:171], v[62:65]
	v_mfma_f32_16x16x32_bf16 v[58:61], v[154:157], v[168:171], v[58:61]
	v_mfma_f32_16x16x32_bf16 v[46:49], v[146:149], v[186:189], v[46:49]
	v_mfma_f32_16x16x32_bf16 v[42:45], v[154:157], v[186:189], v[42:45]
	v_mfma_f32_16x16x32_bf16 v[30:33], v[146:149], v[194:197], v[30:33]
	v_mfma_f32_16x16x32_bf16 v[26:29], v[154:157], v[194:197], v[26:29]
	v_mfma_f32_16x16x32_bf16 v[14:17], v[146:149], v[202:205], v[14:17]
	v_mfma_f32_16x16x32_bf16 v[10:13], v[154:157], v[202:205], v[10:13]
	v_mfma_f32_16x16x32_bf16 v[62:65], v[150:153], v[172:175], v[62:65]
	v_mfma_f32_16x16x32_bf16 v[58:61], v[158:161], v[172:175], v[58:61]
	v_mfma_f32_16x16x32_bf16 v[46:49], v[150:153], v[190:193], v[46:49]
	v_mfma_f32_16x16x32_bf16 v[42:45], v[158:161], v[190:193], v[42:45]
	v_mfma_f32_16x16x32_bf16 v[30:33], v[150:153], v[198:201], v[30:33]
	v_mfma_f32_16x16x32_bf16 v[26:29], v[158:161], v[198:201], v[26:29]
	v_mfma_f32_16x16x32_bf16 v[14:17], v[150:153], v[206:209], v[14:17]
	v_mfma_f32_16x16x32_bf16 v[10:13], v[158:161], v[206:209], v[10:13]
	s_barrier
	s_add_u32 s16, s16, 0x80080
	s_addc_u32 s17, s17, 0
	s_add_i32 s18, s18, s29
	s_mov_b32 m0, s18
	s_nop 0
	global_load_lds_dwordx4 v132, s[16:17]
	s_add_i32 m0, s18, 0x2000
	s_nop 0
	global_load_lds_dwordx4 v136, s[16:17]
	s_waitcnt vmcnt(6)
	s_barrier
	v_mfma_f32_16x16x32_bf16 v[54:57], v[210:213], v[168:171], v[54:57]
	v_mfma_f32_16x16x32_bf16 v[50:53], v[218:221], v[168:171], v[50:53]
	v_mfma_f32_16x16x32_bf16 v[38:41], v[210:213], v[186:189], v[38:41]
	v_mfma_f32_16x16x32_bf16 v[34:37], v[218:221], v[186:189], v[34:37]
	v_mfma_f32_16x16x32_bf16 v[22:25], v[210:213], v[194:197], v[22:25]
	v_mfma_f32_16x16x32_bf16 v[18:21], v[218:221], v[194:197], v[18:21]
	v_mfma_f32_16x16x32_bf16 v[6:9], v[210:213], v[202:205], v[6:9]
	v_mfma_f32_16x16x32_bf16 v[2:5], v[218:221], v[202:205], v[2:5]
	v_mfma_f32_16x16x32_bf16 v[54:57], v[214:217], v[172:175], v[54:57]
	v_mfma_f32_16x16x32_bf16 v[50:53], v[222:225], v[172:175], v[50:53]
	v_mfma_f32_16x16x32_bf16 v[38:41], v[214:217], v[190:193], v[38:41]
	v_mfma_f32_16x16x32_bf16 v[34:37], v[222:225], v[190:193], v[34:37]
	v_mfma_f32_16x16x32_bf16 v[22:25], v[214:217], v[198:201], v[22:25]
	v_mfma_f32_16x16x32_bf16 v[18:21], v[222:225], v[198:201], v[18:21]
	v_mfma_f32_16x16x32_bf16 v[6:9], v[214:217], v[206:209], v[6:9]
	v_mfma_f32_16x16x32_bf16 v[2:5], v[222:225], v[206:209], v[2:5]
	s_barrier
	s_add_i32 s47, s47, 2
	s_add_u32 s6, s6, 0x100
	s_addc_u32 s7, s7, 0
	s_cmp_gt_u32 s47, 29
	s_cbranch_scc0 .LBB0_1408
	s_ashr_i32 s3, s33, 5
	s_mul_hi_i32 s7, s3, 0x9000
	s_mul_i32 s3, s3, 0x9000
	v_lshl_or_b32 v168, s43, 8, v165
	s_add_u32 s6, s36, s3
	s_addc_u32 s7, s37, s7
	v_ashrrev_i32_e32 v169, 31, v168
	v_lshl_add_u64 v[162:163], v[168:169], 2, s[6:7]
	global_load_dwordx4 v[142:145], v[162:163], off offset:16
	global_load_dwordx4 v[146:149], v[162:163], off
	v_mov_b32_e32 v158, v162
	v_mov_b32_e32 v159, v163
	v_lshl_add_u32 v162, s33, 8, v1
	v_ashrrev_i32_e32 v163, 31, v162
	v_lshlrev_b64 v[152:153], 12, v[162:163]
	v_lshl_add_u64 v[152:153], s[8:9], 0, v[152:153]
	v_lshl_add_u64 v[152:153], v[168:169], 1, v[152:153]
	v_mov_b32_e32 v156, 0x10000
	v_mov_b32_e32 v157, 0
	global_load_dwordx4 v[174:177], v[152:153], off offset:2048
	global_load_dwordx4 v[186:189], v[152:153], off offset:2304
	v_lshl_add_u64 v[152:153], v[152:153], 0, v[156:157]
	global_load_dwordx4 v[190:193], v[152:153], off offset:2048
	global_load_dwordx4 v[194:197], v[152:153], off offset:2304
	v_lshl_add_u64 v[152:153], v[152:153], 0, v[156:157]
	global_load_dwordx4 v[198:201], v[152:153], off offset:2048
	global_load_dwordx4 v[202:205], v[152:153], off offset:2304
	v_lshl_add_u64 v[152:153], v[152:153], 0, v[156:157]
	global_load_dwordx4 v[206:209], v[152:153], off offset:2048
	global_load_dwordx4 v[210:213], v[152:153], off offset:2304
	v_mov_b32_e32 v156, 0x50000
	v_lshl_add_u64 v[152:153], v[152:153], 0, v[156:157]
	v_mov_b32_e32 v156, 0x10000
	global_load_dwordx4 v[214:217], v[152:153], off offset:2048
	global_load_dwordx4 v[218:221], v[152:153], off offset:2304
	v_lshl_add_u64 v[152:153], v[152:153], 0, v[156:157]
	global_load_dwordx4 v[222:225], v[152:153], off offset:2048
	global_load_dwordx4 v[226:229], v[152:153], off offset:2304
	v_lshl_add_u64 v[152:153], v[152:153], 0, v[156:157]
	global_load_dwordx4 v[230:233], v[152:153], off offset:2048
	global_load_dwordx4 v[236:239], v[152:153], off offset:2304
	v_lshl_add_u64 v[152:153], v[152:153], 0, v[156:157]
	global_load_dwordx4 v[246:249], v[152:153], off offset:2048
	global_load_dwordx4 v[250:253], v[152:153], off offset:2304
	s_mov_b64 s[6:7], 0x80000
	s_and_b64 vcc, exec, s[4:5]
	s_mov_b32 s43, s2
	s_mov_b64 s[16:17], s[12:13]
	s_mov_b64 s[14:15], s[10:11]
	s_waitcnt vmcnt(16)
	v_pk_add_f32 v[150:151], v[144:145], 1.0 op_sel_hi:[1,0]
	v_pk_add_f32 v[154:155], v[142:143], 1.0 op_sel_hi:[1,0]
	global_load_dwordx4 v[142:145], v[158:159], off offset:512
	global_load_dwordx4 v[158:161], v[158:159], off offset:528
	v_pk_add_f32 v[156:157], v[146:147], 1.0 op_sel_hi:[1,0]
	v_pk_add_f32 v[152:153], v[148:149], 1.0 op_sel_hi:[1,0]
	s_mov_b32 s33, s42
	s_waitcnt vmcnt(0)
	v_pk_add_f32 v[146:147], v[144:145], 1.0 op_sel_hi:[1,0]
	v_pk_add_f32 v[144:145], v[158:159], 1.0 op_sel_hi:[1,0]
	v_lshlrev_b64 v[158:159], 12, v[162:163]
	v_pk_add_f32 v[148:149], v[142:143], 1.0 op_sel_hi:[1,0]
	v_pk_add_f32 v[142:143], v[160:161], 1.0 op_sel_hi:[1,0]
	v_lshl_add_u64 v[158:159], s[8:9], 0, v[158:159]
	v_lshlrev_b64 v[160:161], 1, v[168:169]
	v_lshl_add_u64 v[158:159], v[158:159], 0, v[160:161]
	v_mov_b32_e32 v168, v174
	v_mov_b32_e32 v169, v175
	v_mov_b32_e32 v170, v176
	v_mov_b32_e32 v171, v177
	s_nop 0
	v_lshlrev_b32_e32 v172, 16, v168
	v_and_b32_e32 v173, 0xffff0000, v168
	v_lshlrev_b32_e32 v168, 16, v169
	v_and_b32_e32 v169, 0xffff0000, v169
	v_pk_fma_f32 v[128:129], v[128:129], v[152:153], v[168:169]
	v_lshlrev_b32_e32 v168, 16, v170
	v_and_b32_e32 v169, 0xffff0000, v170
	v_pk_fma_f32 v[168:169], v[122:123], v[154:155], v[168:169]
	v_lshlrev_b32_e32 v122, 16, v171
	v_and_b32_e32 v123, 0xffff0000, v171
	v_pk_fma_f32 v[126:127], v[126:127], v[156:157], v[172:173]
	v_pk_fma_f32 v[170:171], v[124:125], v[150:151], v[122:123]
	v_cvt_pk_bf16_f32 v122, v126, v127
	v_cvt_pk_bf16_f32 v123, v128, v129
	v_cvt_pk_bf16_f32 v124, v168, v169
	v_cvt_pk_bf16_f32 v125, v170, v171
	global_store_dwordx4 v[158:159], v[122:125], off offset:2048
	s_nop 1
	v_mov_b32_e32 v122, v186
	v_mov_b32_e32 v123, v187
	v_mov_b32_e32 v124, v188
	v_mov_b32_e32 v125, v189
	s_nop 0
	v_lshlrev_b32_e32 v126, 16, v122
	v_and_b32_e32 v127, 0xffff0000, v122
	v_lshlrev_b32_e32 v122, 16, v123
	v_and_b32_e32 v123, 0xffff0000, v123
	v_pk_fma_f32 v[120:121], v[120:121], v[146:147], v[122:123]
	v_lshlrev_b32_e32 v122, 16, v124
	v_and_b32_e32 v123, 0xffff0000, v124
	v_pk_fma_f32 v[122:123], v[114:115], v[144:145], v[122:123]
	v_lshlrev_b32_e32 v114, 16, v125
	v_and_b32_e32 v115, 0xffff0000, v125
	v_pk_fma_f32 v[118:119], v[118:119], v[148:149], v[126:127]
	v_pk_fma_f32 v[124:125], v[116:117], v[142:143], v[114:115]
	v_cvt_pk_bf16_f32 v114, v118, v119
	v_cvt_pk_bf16_f32 v115, v120, v121
	v_cvt_pk_bf16_f32 v116, v122, v123
	v_cvt_pk_bf16_f32 v117, v124, v125
	global_store_dwordx4 v[158:159], v[114:117], off offset:2304
	s_nop 1
	v_or_b32_e32 v114, 16, v162
	v_ashrrev_i32_e32 v115, 31, v114
	v_lshlrev_b64 v[114:115], 12, v[114:115]
	v_lshl_add_u64 v[114:115], s[8:9], 0, v[114:115]
	v_lshl_add_u64 v[118:119], v[114:115], 0, v[160:161]
	v_mov_b32_e32 v114, v190
	v_mov_b32_e32 v115, v191
	v_mov_b32_e32 v116, v192
	v_mov_b32_e32 v117, v193
	s_nop 0
	v_lshlrev_b32_e32 v120, 16, v114
	v_and_b32_e32 v121, 0xffff0000, v114
	v_lshlrev_b32_e32 v114, 16, v115
	v_and_b32_e32 v115, 0xffff0000, v115
	v_pk_fma_f32 v[112:113], v[112:113], v[152:153], v[114:115]
	v_lshlrev_b32_e32 v114, 16, v116
	v_and_b32_e32 v115, 0xffff0000, v116
	v_pk_fma_f32 v[114:115], v[106:107], v[154:155], v[114:115]
	v_lshlrev_b32_e32 v106, 16, v117
	v_and_b32_e32 v107, 0xffff0000, v117
	v_pk_fma_f32 v[110:111], v[110:111], v[156:157], v[120:121]
	v_pk_fma_f32 v[116:117], v[108:109], v[150:151], v[106:107]
	v_cvt_pk_bf16_f32 v106, v110, v111
	v_cvt_pk_bf16_f32 v107, v112, v113
	v_cvt_pk_bf16_f32 v108, v114, v115
	v_cvt_pk_bf16_f32 v109, v116, v117
	global_store_dwordx4 v[118:119], v[106:109], off offset:2048
	s_nop 1
	v_mov_b32_e32 v106, v194
	v_mov_b32_e32 v107, v195
	v_mov_b32_e32 v108, v196
	v_mov_b32_e32 v109, v197
	s_nop 0
	v_lshlrev_b32_e32 v110, 16, v106
	v_and_b32_e32 v111, 0xffff0000, v106
	v_lshlrev_b32_e32 v106, 16, v107
	v_and_b32_e32 v107, 0xffff0000, v107
	v_pk_fma_f32 v[104:105], v[104:105], v[146:147], v[106:107]
	v_lshlrev_b32_e32 v106, 16, v108
	v_and_b32_e32 v107, 0xffff0000, v108
	v_pk_fma_f32 v[106:107], v[98:99], v[144:145], v[106:107]
	v_lshlrev_b32_e32 v98, 16, v109
	v_and_b32_e32 v99, 0xffff0000, v109
	v_pk_fma_f32 v[102:103], v[102:103], v[148:149], v[110:111]
	v_pk_fma_f32 v[108:109], v[100:101], v[142:143], v[98:99]
	v_cvt_pk_bf16_f32 v98, v102, v103
	v_cvt_pk_bf16_f32 v99, v104, v105
	v_cvt_pk_bf16_f32 v100, v106, v107
	v_cvt_pk_bf16_f32 v101, v108, v109
	global_store_dwordx4 v[118:119], v[98:101], off offset:2304
	s_nop 1
	v_or_b32_e32 v98, 32, v162
	v_ashrrev_i32_e32 v99, 31, v98
	v_lshlrev_b64 v[98:99], 12, v[98:99]
	v_lshl_add_u64 v[98:99], s[8:9], 0, v[98:99]
	v_lshl_add_u64 v[102:103], v[98:99], 0, v[160:161]
	v_mov_b32_e32 v98, v198
	v_mov_b32_e32 v99, v199
	v_mov_b32_e32 v100, v200
	v_mov_b32_e32 v101, v201
	s_nop 0
	v_lshlrev_b32_e32 v104, 16, v98
	v_and_b32_e32 v105, 0xffff0000, v98
	v_lshlrev_b32_e32 v98, 16, v99
	v_and_b32_e32 v99, 0xffff0000, v99
	v_pk_fma_f32 v[96:97], v[96:97], v[152:153], v[98:99]
	v_lshlrev_b32_e32 v98, 16, v100
	v_and_b32_e32 v99, 0xffff0000, v100
	v_pk_fma_f32 v[98:99], v[90:91], v[154:155], v[98:99]
	v_lshlrev_b32_e32 v90, 16, v101
	v_and_b32_e32 v91, 0xffff0000, v101
	v_pk_fma_f32 v[94:95], v[94:95], v[156:157], v[104:105]
	v_pk_fma_f32 v[100:101], v[92:93], v[150:151], v[90:91]
	v_cvt_pk_bf16_f32 v90, v94, v95
	v_cvt_pk_bf16_f32 v91, v96, v97
	v_cvt_pk_bf16_f32 v92, v98, v99
	v_cvt_pk_bf16_f32 v93, v100, v101
	global_store_dwordx4 v[102:103], v[90:93], off offset:2048
	s_nop 1
	v_mov_b32_e32 v90, v202
	v_mov_b32_e32 v91, v203
	v_mov_b32_e32 v92, v204
	v_mov_b32_e32 v93, v205
	s_nop 0
	v_lshlrev_b32_e32 v94, 16, v90
	v_and_b32_e32 v95, 0xffff0000, v90
	v_lshlrev_b32_e32 v90, 16, v91
	v_and_b32_e32 v91, 0xffff0000, v91
	v_pk_fma_f32 v[88:89], v[88:89], v[146:147], v[90:91]
	v_lshlrev_b32_e32 v90, 16, v92
	v_and_b32_e32 v91, 0xffff0000, v92
	v_pk_fma_f32 v[90:91], v[82:83], v[144:145], v[90:91]
	v_lshlrev_b32_e32 v82, 16, v93
	v_and_b32_e32 v83, 0xffff0000, v93
	v_pk_fma_f32 v[86:87], v[86:87], v[148:149], v[94:95]
	v_pk_fma_f32 v[92:93], v[84:85], v[142:143], v[82:83]
	v_cvt_pk_bf16_f32 v82, v86, v87
	v_cvt_pk_bf16_f32 v83, v88, v89
	v_cvt_pk_bf16_f32 v84, v90, v91
	v_cvt_pk_bf16_f32 v85, v92, v93
	global_store_dwordx4 v[102:103], v[82:85], off offset:2304
	s_nop 1
	v_or_b32_e32 v82, 48, v162
	v_ashrrev_i32_e32 v83, 31, v82
	v_lshlrev_b64 v[82:83], 12, v[82:83]
	v_lshl_add_u64 v[82:83], s[8:9], 0, v[82:83]
	v_lshl_add_u64 v[82:83], v[82:83], 0, v[160:161]
	v_mov_b32_e32 v84, v206
	v_mov_b32_e32 v85, v207
	v_mov_b32_e32 v86, v208
	v_mov_b32_e32 v87, v209
	s_nop 0
	v_lshlrev_b32_e32 v88, 16, v84
	v_and_b32_e32 v89, 0xffff0000, v84
	v_lshlrev_b32_e32 v84, 16, v85
	v_and_b32_e32 v85, 0xffff0000, v85
	v_pk_fma_f32 v[80:81], v[80:81], v[152:153], v[84:85]
	v_lshlrev_b32_e32 v84, 16, v86
	v_and_b32_e32 v85, 0xffff0000, v86
	v_pk_fma_f32 v[84:85], v[74:75], v[154:155], v[84:85]
	v_lshlrev_b32_e32 v74, 16, v87
	v_and_b32_e32 v75, 0xffff0000, v87
	v_pk_fma_f32 v[78:79], v[78:79], v[156:157], v[88:89]
	v_pk_fma_f32 v[86:87], v[76:77], v[150:151], v[74:75]
	v_cvt_pk_bf16_f32 v74, v78, v79
	v_cvt_pk_bf16_f32 v75, v80, v81
	v_cvt_pk_bf16_f32 v76, v84, v85
	v_cvt_pk_bf16_f32 v77, v86, v87
	global_store_dwordx4 v[82:83], v[74:77], off offset:2048
	s_nop 1
	v_mov_b32_e32 v74, v210
	v_mov_b32_e32 v75, v211
	v_mov_b32_e32 v76, v212
	v_mov_b32_e32 v77, v213
	s_nop 0
	v_lshlrev_b32_e32 v78, 16, v74
	v_and_b32_e32 v79, 0xffff0000, v74
	v_lshlrev_b32_e32 v74, 16, v75
	v_and_b32_e32 v75, 0xffff0000, v75
	v_pk_fma_f32 v[72:73], v[72:73], v[146:147], v[74:75]
	v_lshlrev_b32_e32 v74, 16, v76
	v_and_b32_e32 v75, 0xffff0000, v76
	v_pk_fma_f32 v[74:75], v[66:67], v[144:145], v[74:75]
	v_lshlrev_b32_e32 v66, 16, v77
	v_and_b32_e32 v67, 0xffff0000, v77
	v_pk_fma_f32 v[70:71], v[70:71], v[148:149], v[78:79]
	v_pk_fma_f32 v[76:77], v[68:69], v[142:143], v[66:67]
	v_cvt_pk_bf16_f32 v66, v70, v71
	v_cvt_pk_bf16_f32 v67, v72, v73
	v_cvt_pk_bf16_f32 v68, v74, v75
	v_cvt_pk_bf16_f32 v69, v76, v77
	v_lshl_add_u64 v[70:71], v[158:159], 0, s[6:7]
	global_store_dwordx4 v[82:83], v[66:69], off offset:2304
	s_nop 1
	v_mov_b32_e32 v66, v214
	v_mov_b32_e32 v67, v215
	v_mov_b32_e32 v68, v216
	v_mov_b32_e32 v69, v217
	s_mov_b64 s[6:7], 0x90000
	s_nop 0
	v_lshlrev_b32_e32 v72, 16, v66
	v_and_b32_e32 v73, 0xffff0000, v66
	v_lshlrev_b32_e32 v66, 16, v67
	v_and_b32_e32 v67, 0xffff0000, v67
	v_pk_fma_f32 v[64:65], v[64:65], v[152:153], v[66:67]
	v_lshlrev_b32_e32 v66, 16, v68
	v_and_b32_e32 v67, 0xffff0000, v68
	v_pk_fma_f32 v[66:67], v[58:59], v[154:155], v[66:67]
	v_lshlrev_b32_e32 v58, 16, v69
	v_and_b32_e32 v59, 0xffff0000, v69
	v_pk_fma_f32 v[62:63], v[62:63], v[156:157], v[72:73]
	v_pk_fma_f32 v[68:69], v[60:61], v[150:151], v[58:59]
	v_cvt_pk_bf16_f32 v58, v62, v63
	v_cvt_pk_bf16_f32 v59, v64, v65
	v_cvt_pk_bf16_f32 v60, v66, v67
	v_cvt_pk_bf16_f32 v61, v68, v69
	global_store_dwordx4 v[70:71], v[58:61], off offset:2048
	s_nop 1
	v_mov_b32_e32 v58, v218
	v_mov_b32_e32 v59, v219
	v_mov_b32_e32 v60, v220
	v_mov_b32_e32 v61, v221
	s_nop 0
	v_lshlrev_b32_e32 v62, 16, v58
	v_and_b32_e32 v63, 0xffff0000, v58
	v_lshlrev_b32_e32 v58, 16, v59
	v_and_b32_e32 v59, 0xffff0000, v59
	v_pk_fma_f32 v[56:57], v[56:57], v[146:147], v[58:59]
	v_lshlrev_b32_e32 v58, 16, v60
	v_and_b32_e32 v59, 0xffff0000, v60
	v_pk_fma_f32 v[58:59], v[50:51], v[144:145], v[58:59]
	v_lshlrev_b32_e32 v50, 16, v61
	v_and_b32_e32 v51, 0xffff0000, v61
	v_pk_fma_f32 v[54:55], v[54:55], v[148:149], v[62:63]
	v_pk_fma_f32 v[60:61], v[52:53], v[142:143], v[50:51]
	v_cvt_pk_bf16_f32 v50, v54, v55
	v_cvt_pk_bf16_f32 v51, v56, v57
	v_cvt_pk_bf16_f32 v52, v58, v59
	v_cvt_pk_bf16_f32 v53, v60, v61
	v_lshl_add_u64 v[54:55], v[158:159], 0, s[6:7]
	global_store_dwordx4 v[70:71], v[50:53], off offset:2304
	s_nop 1
	v_mov_b32_e32 v50, v222
	v_mov_b32_e32 v51, v223
	v_mov_b32_e32 v52, v224
	v_mov_b32_e32 v53, v225
	s_mov_b64 s[6:7], 0xa0000
	s_nop 0
	v_lshlrev_b32_e32 v56, 16, v50
	v_and_b32_e32 v57, 0xffff0000, v50
	v_lshlrev_b32_e32 v50, 16, v51
	v_and_b32_e32 v51, 0xffff0000, v51
	v_pk_fma_f32 v[48:49], v[48:49], v[152:153], v[50:51]
	v_lshlrev_b32_e32 v50, 16, v52
	v_and_b32_e32 v51, 0xffff0000, v52
	v_pk_fma_f32 v[50:51], v[42:43], v[154:155], v[50:51]
	v_lshlrev_b32_e32 v42, 16, v53
	v_and_b32_e32 v43, 0xffff0000, v53
	v_pk_fma_f32 v[46:47], v[46:47], v[156:157], v[56:57]
	v_pk_fma_f32 v[52:53], v[44:45], v[150:151], v[42:43]
	v_cvt_pk_bf16_f32 v42, v46, v47
	v_cvt_pk_bf16_f32 v43, v48, v49
	v_cvt_pk_bf16_f32 v44, v50, v51
	v_cvt_pk_bf16_f32 v45, v52, v53
	global_store_dwordx4 v[54:55], v[42:45], off offset:2048
	s_nop 1
	v_mov_b32_e32 v42, v226
	v_mov_b32_e32 v43, v227
	v_mov_b32_e32 v44, v228
	v_mov_b32_e32 v45, v229
	s_nop 0
	v_lshlrev_b32_e32 v46, 16, v42
	v_and_b32_e32 v47, 0xffff0000, v42
	v_lshlrev_b32_e32 v42, 16, v43
	v_and_b32_e32 v43, 0xffff0000, v43
	v_pk_fma_f32 v[40:41], v[40:41], v[146:147], v[42:43]
	v_lshlrev_b32_e32 v42, 16, v44
	v_and_b32_e32 v43, 0xffff0000, v44
	v_pk_fma_f32 v[42:43], v[34:35], v[144:145], v[42:43]
	v_lshlrev_b32_e32 v34, 16, v45
	v_and_b32_e32 v35, 0xffff0000, v45
	v_pk_fma_f32 v[38:39], v[38:39], v[148:149], v[46:47]
	v_pk_fma_f32 v[44:45], v[36:37], v[142:143], v[34:35]
	v_cvt_pk_bf16_f32 v34, v38, v39
	v_cvt_pk_bf16_f32 v35, v40, v41
	v_cvt_pk_bf16_f32 v36, v42, v43
	v_cvt_pk_bf16_f32 v37, v44, v45
	v_lshl_add_u64 v[38:39], v[158:159], 0, s[6:7]
	global_store_dwordx4 v[54:55], v[34:37], off offset:2304
	s_nop 1
	v_mov_b32_e32 v34, v230
	v_mov_b32_e32 v35, v231
	v_mov_b32_e32 v36, v232
	v_mov_b32_e32 v37, v233
	s_mov_b64 s[6:7], 0xb0000
	s_nop 0
	v_lshlrev_b32_e32 v40, 16, v34
	v_and_b32_e32 v41, 0xffff0000, v34
	v_lshlrev_b32_e32 v34, 16, v35
	v_and_b32_e32 v35, 0xffff0000, v35
	v_pk_fma_f32 v[32:33], v[32:33], v[152:153], v[34:35]
	v_lshlrev_b32_e32 v34, 16, v36
	v_and_b32_e32 v35, 0xffff0000, v36
	v_pk_fma_f32 v[34:35], v[26:27], v[154:155], v[34:35]
	v_lshlrev_b32_e32 v26, 16, v37
	v_and_b32_e32 v27, 0xffff0000, v37
	v_pk_fma_f32 v[30:31], v[30:31], v[156:157], v[40:41]
	v_pk_fma_f32 v[36:37], v[28:29], v[150:151], v[26:27]
	v_cvt_pk_bf16_f32 v26, v30, v31
	v_cvt_pk_bf16_f32 v27, v32, v33
	v_cvt_pk_bf16_f32 v28, v34, v35
	v_cvt_pk_bf16_f32 v29, v36, v37
	global_store_dwordx4 v[38:39], v[26:29], off offset:2048
	s_nop 1
	v_mov_b32_e32 v26, v236
	v_mov_b32_e32 v27, v237
	v_mov_b32_e32 v28, v238
	v_mov_b32_e32 v29, v239
	s_nop 0
	v_lshlrev_b32_e32 v30, 16, v26
	v_and_b32_e32 v31, 0xffff0000, v26
	v_lshlrev_b32_e32 v26, 16, v27
	v_and_b32_e32 v27, 0xffff0000, v27
	v_pk_fma_f32 v[24:25], v[24:25], v[146:147], v[26:27]
	v_lshlrev_b32_e32 v26, 16, v28
	v_and_b32_e32 v27, 0xffff0000, v28
	v_pk_fma_f32 v[26:27], v[18:19], v[144:145], v[26:27]
	v_lshlrev_b32_e32 v18, 16, v29
	v_and_b32_e32 v19, 0xffff0000, v29
	v_pk_fma_f32 v[22:23], v[22:23], v[148:149], v[30:31]
	v_pk_fma_f32 v[28:29], v[20:21], v[142:143], v[18:19]
	v_cvt_pk_bf16_f32 v18, v22, v23
	v_cvt_pk_bf16_f32 v19, v24, v25
	v_cvt_pk_bf16_f32 v20, v26, v27
	v_cvt_pk_bf16_f32 v21, v28, v29
	global_store_dwordx4 v[38:39], v[18:21], off offset:2304
	s_nop 1
	v_lshl_add_u64 v[18:19], v[158:159], 0, s[6:7]
	v_mov_b32_e32 v20, v246
	v_mov_b32_e32 v21, v247
	v_mov_b32_e32 v22, v248
	v_mov_b32_e32 v23, v249
	s_nop 0
	v_lshlrev_b32_e32 v24, 16, v20
	v_and_b32_e32 v25, 0xffff0000, v20
	v_lshlrev_b32_e32 v20, 16, v21
	v_and_b32_e32 v21, 0xffff0000, v21
	v_pk_fma_f32 v[16:17], v[16:17], v[152:153], v[20:21]
	v_lshlrev_b32_e32 v20, 16, v22
	v_and_b32_e32 v21, 0xffff0000, v22
	v_pk_fma_f32 v[20:21], v[10:11], v[154:155], v[20:21]
	v_lshlrev_b32_e32 v10, 16, v23
	v_and_b32_e32 v11, 0xffff0000, v23
	v_pk_fma_f32 v[14:15], v[14:15], v[156:157], v[24:25]
	v_pk_fma_f32 v[22:23], v[12:13], v[150:151], v[10:11]
	v_cvt_pk_bf16_f32 v10, v14, v15
	v_cvt_pk_bf16_f32 v11, v16, v17
	v_cvt_pk_bf16_f32 v12, v20, v21
	v_cvt_pk_bf16_f32 v13, v22, v23
	global_store_dwordx4 v[18:19], v[10:13], off offset:2048
	s_nop 1
	v_mov_b32_e32 v10, v250
	v_mov_b32_e32 v11, v251
	v_mov_b32_e32 v12, v252
	v_mov_b32_e32 v13, v253
	s_nop 0
	v_lshlrev_b32_e32 v14, 16, v10
	v_and_b32_e32 v15, 0xffff0000, v10
	v_lshlrev_b32_e32 v10, 16, v11
	v_and_b32_e32 v11, 0xffff0000, v11
	v_pk_fma_f32 v[8:9], v[8:9], v[146:147], v[10:11]
	v_lshlrev_b32_e32 v10, 16, v12
	v_and_b32_e32 v11, 0xffff0000, v12
	v_pk_fma_f32 v[10:11], v[2:3], v[144:145], v[10:11]
	v_lshlrev_b32_e32 v2, 16, v13
	v_and_b32_e32 v3, 0xffff0000, v13
	v_pk_fma_f32 v[6:7], v[6:7], v[148:149], v[14:15]
	v_pk_fma_f32 v[12:13], v[4:5], v[142:143], v[2:3]
	v_cvt_pk_bf16_f32 v2, v6, v7
	v_cvt_pk_bf16_f32 v3, v8, v9
	v_cvt_pk_bf16_f32 v4, v10, v11
	v_cvt_pk_bf16_f32 v5, v12, v13
	global_store_dwordx4 v[18:19], v[2:5], off offset:2304
	s_cbranch_vccz .LBB0_1399
	s_waitcnt vmcnt(0)
	s_cmpk_gt_u32 s22, 0xff
	s_cbranch_scc1 .LBB0_1412
	s_barrier
